# f32 residual epilogue of wout and ffn2_dense rewritten: per-wave LDS transpose, batched coalesced xres loads, full-row stores
# speedup vs baseline: 1.2419x; 1.0145x over previous
; DI f16v mfma32(h8v a, h8v b, f16v c) { return __builtin_amdgcn_mfma_f32_32x32x16_f16(a, b, c, 0, 0, 0); }
; template <bool GATHER>
; DI void gemm256_main(const h16* __restrict__ A, int lda, const int* __restrict__ idx, int m0,
;                      const h16* __restrict__ B, int ldb, int n0, int K, h16* lds, f16v (&acc)[4][2]) {
;     ...
;   for (int kt = 0; kt < nk; ++kt) {
;     const h16* As = lds + (kt & 1) * (512 * LDH);
;     const h16* Bs = As + 256 * LDH;
;     h16* Wn = lds + ((kt & 1) ^ 1) * (512 * LDH);
;     if (kt + 1 < nk) {
; #pragma unroll
;       for (int i = 0; i < 4; ++i) { *(u4v*)&Wn[lr * LDH + lc + 8 * i] = ra[i]; *(u4v*)&Wn[(256 + lr) * LDH + lc + 8 * i] = rb[i]; }
;     }
;     if (kt + 2 < nk) {
; #pragma unroll
;       for (int i = 0; i < 4; ++i) { ra[i] = *(const u4v*)(AP_ + 8 * i); rb[i] = *(const u4v*)(BP_ + 8 * i); }
;       ao += 64; bo += 64;
;     }
; #pragma unroll
;     for (int ks = 0; ks < 4; ++ks) {
;       h8v af[4], bf[2];
; #pragma unroll
;       for (int i = 0; i < 4; ++i) af[i] = *(const h8v*)&As[(wm * 128 + i * 32 + (lane & 31)) * LDH + ks * 16 + 8 * (lane >> 5)];
; #pragma unroll
;       for (int j = 0; j < 2; ++j) bf[j] = *(const h8v*)&Bs[(wn * 64 + j * 32 + (lane & 31)) * LDH + ks * 16 + 8 * (lane >> 5)];
; #pragma unroll
;       for (int i = 0; i < 4; ++i)
; #pragma unroll
;         for (int j = 0; j < 2; ++j) acc[i][j] = mfma32(bf[j], af[i], acc[i][j]);
;     }
;     __syncthreads();
;   }
.LBB0_1355:
	s_and_b32 s8, s7, 1
	s_mul_i32 s9, s8, 0x12000
	s_xor_b32 s8, s8, 1
	s_mul_i32 s8, s8, 0x12000
	v_add_u32_e32 v163, s9, v175
	v_add_u32_e32 v165, s8, v176
	v_add_u32_e32 v177, v163, v171
	v_add_u32_e32 v163, v163, v1
	s_waitcnt vmcnt(4)
	ds_write_b128 v165, v[150:153]
	s_waitcnt vmcnt(0)
	ds_write_b128 v165, v[158:161] offset:36864
	ds_write_b128 v165, v[142:145] offset:16
	ds_write_b128 v165, v[154:157] offset:36880
	ds_write_b128 v165, v[134:137] offset:32
	ds_write_b128 v165, v[146:149] offset:36896
	ds_write_b128 v165, v[130:133] offset:48
	ds_write_b128 v165, v[138:141] offset:36912
	ds_read_b128 v[130:133], v163 offset:36864
	ds_read_b128 v[134:137], v177
	ds_read_b128 v[138:141], v177 offset:32
	ds_read_b128 v[142:145], v163 offset:36896
	ds_read_b128 v[146:149], v163 offset:41472
	ds_read_b128 v[150:153], v163 offset:41504
	s_waitcnt lgkmcnt(4)
	v_mfma_f32_32x32x16_f16 v[114:129], v[130:133], v[134:137], v[114:129]
	v_mov_b32_e32 v165, v0
	s_add_i32 s7, s7, 1
	s_cmp_eq_u32 s7, 14
	s_waitcnt lgkmcnt(1)
	v_mfma_f32_32x32x16_f16 v[98:113], v[146:149], v[134:137], v[98:113]
	ds_read_b128 v[134:137], v177 offset:4608
	ds_read_b128 v[154:157], v177 offset:4640
	s_waitcnt lgkmcnt(1)
	v_mfma_f32_32x32x16_f16 v[82:97], v[130:133], v[134:137], v[82:97]
	v_mfma_f32_32x32x16_f16 v[66:81], v[146:149], v[134:137], v[66:81]
	ds_read_b128 v[134:137], v177 offset:9216
	ds_read_b128 v[158:161], v177 offset:9248
	s_waitcnt lgkmcnt(1)
	v_mfma_f32_32x32x16_f16 v[50:65], v[130:133], v[134:137], v[50:65]
	v_mfma_f32_32x32x16_f16 v[34:49], v[146:149], v[134:137], v[34:49]
	ds_read_b128 v[134:137], v177 offset:13824
	ds_read_b128 v[216:219], v177 offset:13856
	s_waitcnt lgkmcnt(1)
	v_mfma_f32_32x32x16_f16 v[18:33], v[130:133], v[134:137], v[18:33]
	v_mfma_f32_32x32x16_f16 v[2:17], v[146:149], v[134:137], v[2:17]
	v_mfma_f32_32x32x16_f16 v[114:129], v[142:145], v[138:141], v[114:129]
	v_mfma_f32_32x32x16_f16 v[98:113], v[150:153], v[138:141], v[98:113]
	v_mfma_f32_32x32x16_f16 v[82:97], v[142:145], v[154:157], v[82:97]
	v_mfma_f32_32x32x16_f16 v[66:81], v[150:153], v[154:157], v[66:81]
	v_mfma_f32_32x32x16_f16 v[50:65], v[142:145], v[158:161], v[50:65]
	v_mfma_f32_32x32x16_f16 v[34:49], v[150:153], v[158:161], v[34:49]
	ds_read_b128 v[130:133], v163 offset:36928
	ds_read_b128 v[134:137], v177 offset:64
	ds_read_b128 v[138:141], v177 offset:96
	ds_read_b128 v[158:161], v163 offset:36960
	s_waitcnt lgkmcnt(4)
	v_mfma_f32_32x32x16_f16 v[18:33], v[142:145], v[216:219], v[18:33]
	v_mfma_f32_32x32x16_f16 v[2:17], v[150:153], v[216:219], v[2:17]
	ds_read_b128 v[142:145], v163 offset:41536
	ds_read_b128 v[216:219], v163 offset:41568
	v_mov_b32_e32 v163, v0
	v_lshl_add_u64 v[178:179], v[162:163], 1, s[16:17]
	v_add_u32_e32 v162, 64, v162
	s_waitcnt lgkmcnt(4)
	v_mfma_f32_32x32x16_f16 v[114:129], v[130:133], v[134:137], v[114:129]
	s_waitcnt lgkmcnt(1)
	v_mfma_f32_32x32x16_f16 v[98:113], v[142:145], v[134:137], v[98:113]
	ds_read_b128 v[134:137], v177 offset:4672
	ds_read_b128 v[146:149], v177 offset:4704
	s_waitcnt lgkmcnt(1)
	v_mfma_f32_32x32x16_f16 v[82:97], v[130:133], v[134:137], v[82:97]
	v_mfma_f32_32x32x16_f16 v[66:81], v[142:145], v[134:137], v[66:81]
	ds_read_b128 v[134:137], v177 offset:9280
	ds_read_b128 v[150:153], v177 offset:9312
	s_waitcnt lgkmcnt(1)
	v_mfma_f32_32x32x16_f16 v[50:65], v[130:133], v[134:137], v[50:65]
	v_mfma_f32_32x32x16_f16 v[34:49], v[142:145], v[134:137], v[34:49]
	ds_read_b128 v[134:137], v177 offset:13888
	ds_read_b128 v[220:223], v177 offset:13920
	s_waitcnt lgkmcnt(1)
	v_mfma_f32_32x32x16_f16 v[18:33], v[130:133], v[134:137], v[18:33]
	v_mfma_f32_32x32x16_f16 v[114:129], v[158:161], v[138:141], v[114:129]
	v_mfma_f32_32x32x16_f16 v[98:113], v[216:219], v[138:141], v[98:113]
	v_lshl_add_u64 v[138:139], v[164:165], 1, s[30:31]
	v_add_u32_e32 v164, 64, v164
	v_mfma_f32_32x32x16_f16 v[2:17], v[142:145], v[134:137], v[2:17]
	v_mfma_f32_32x32x16_f16 v[82:97], v[158:161], v[146:149], v[82:97]
	v_mfma_f32_32x32x16_f16 v[66:81], v[216:219], v[146:149], v[66:81]
	v_mfma_f32_32x32x16_f16 v[50:65], v[158:161], v[150:153], v[50:65]
	v_mfma_f32_32x32x16_f16 v[34:49], v[216:219], v[150:153], v[34:49]
	global_load_dwordx4 v[130:133], v[138:139], off offset:48
	global_load_dwordx4 v[134:137], v[138:139], off offset:32
	global_load_dwordx4 v[142:145], v[138:139], off offset:16
	global_load_dwordx4 v[150:153], v[138:139], off
	s_nop 0
	global_load_dwordx4 v[138:141], v[178:179], off offset:48
	global_load_dwordx4 v[146:149], v[178:179], off offset:32
	global_load_dwordx4 v[154:157], v[178:179], off offset:16
	s_waitcnt lgkmcnt(0)
	v_mfma_f32_32x32x16_f16 v[18:33], v[158:161], v[220:223], v[18:33]
	global_load_dwordx4 v[158:161], v[178:179], off
	s_barrier
	v_mfma_f32_32x32x16_f16 v[2:17], v[216:219], v[220:223], v[2:17]
	s_cbranch_scc0 .LBB0_1355
; DI f16v mfma32(h8v a, h8v b, f16v c) { return __builtin_amdgcn_mfma_f32_32x32x16_f16(a, b, c, 0, 0, 0); }
; template <bool GATHER>
; DI void gemm256_main(const h16* __restrict__ A, int lda, const int* __restrict__ idx, int m0,
;                      const h16* __restrict__ B, int ldb, int n0, int K, h16* lds, f16v (&acc)[4][2]) {
;     ...
;   for (int kt = 0; kt < nk; ++kt) {
;     const h16* As = lds + (kt & 1) * (512 * LDH);
;     const h16* Bs = As + 256 * LDH;
;     h16* Wn = lds + ((kt & 1) ^ 1) * (512 * LDH);
;     if (kt + 1 < nk) {
; #pragma unroll
;       for (int i = 0; i < 4; ++i) { *(u4v*)&Wn[lr * LDH + lc + 8 * i] = ra[i]; *(u4v*)&Wn[(256 + lr) * LDH + lc + 8 * i] = rb[i]; }
;     }
;     if (kt + 2 < nk) {
; #pragma unroll
;       for (int i = 0; i < 4; ++i) { ra[i] = *(const u4v*)(AP_ + 8 * i); rb[i] = *(const u4v*)(BP_ + 8 * i); }
;       ao += 64; bo += 64;
;     }
; #pragma unroll
;     for (int ks = 0; ks < 4; ++ks) {
;       h8v af[4], bf[2];
; #pragma unroll
;       for (int i = 0; i < 4; ++i) af[i] = *(const h8v*)&As[(wm * 128 + i * 32 + (lane & 31)) * LDH + ks * 16 + 8 * (lane >> 5)];
; #pragma unroll
;       for (int j = 0; j < 2; ++j) bf[j] = *(const h8v*)&Bs[(wn * 64 + j * 32 + (lane & 31)) * LDH + ks * 16 + 8 * (lane >> 5)];
; #pragma unroll
;       for (int i = 0; i < 4; ++i)
; #pragma unroll
;         for (int j = 0; j < 2; ++j) acc[i][j] = mfma32(bf[j], af[i], acc[i][j]);
;     }
;     __syncthreads();
;   }
	v_add_u32_e32 v162, 0x12000, v176
	v_add_u32_e32 v163, 0x1b000, v176
	s_waitcnt vmcnt(4)
	ds_write_b128 v162, v[150:153]
	s_waitcnt vmcnt(0)
	ds_write_b128 v163, v[158:161]
	ds_write_b128 v162, v[142:145] offset:16
	ds_write_b128 v163, v[154:157] offset:16
	ds_write_b128 v162, v[134:137] offset:32
	ds_write_b128 v163, v[146:149] offset:32
	ds_write_b128 v162, v[130:133] offset:48
	ds_write_b128 v163, v[138:141] offset:48
	v_add_u32_e32 v162, v175, v171
	v_add_u32_e32 v163, v175, v1
	ds_read_b128 v[130:133], v162 offset:4608
	ds_read_b128 v[134:137], v162 offset:9216
	ds_read_b128 v[138:141], v162 offset:13824
	ds_read_b128 v[142:145], v163 offset:41472
	ds_read_b128 v[146:149], v162
	ds_read_b128 v[150:153], v162 offset:32
	ds_read_b128 v[154:157], v163 offset:36864
	ds_read_b128 v[158:161], v163 offset:36896
	s_waitcnt lgkmcnt(1)
	v_mfma_f32_32x32x16_f16 v[114:129], v[154:157], v[146:149], v[114:129]
	s_add_i32 s7, 16, 0x12000
	s_add_i32 s8, 16, 0x1b000
	v_readlane_b32 s16, v252, 3
	v_readlane_b32 s18, v252, 5
	v_readlane_b32 s19, v252, 6
	v_readlane_b32 s22, v252, 9
	s_add_i32 s4, s4, s22
	v_mfma_f32_32x32x16_f16 v[98:113], v[142:145], v[146:149], v[98:113]
	s_cmpk_gt_i32 s4, 0xff
	v_readlane_b32 s17, v252, 4
	v_readlane_b32 s20, v252, 7
	v_readlane_b32 s21, v252, 8
	v_readlane_b32 s23, v252, 10
	v_mfma_f32_32x32x16_f16 v[18:33], v[154:157], v[138:141], v[18:33]
	v_mfma_f32_32x32x16_f16 v[2:17], v[142:145], v[138:141], v[2:17]
	v_mfma_f32_32x32x16_f16 v[82:97], v[154:157], v[130:133], v[82:97]
	v_mfma_f32_32x32x16_f16 v[66:81], v[142:145], v[130:133], v[66:81]
	v_mfma_f32_32x32x16_f16 v[50:65], v[154:157], v[134:137], v[50:65]
	v_mfma_f32_32x32x16_f16 v[34:49], v[142:145], v[134:137], v[34:49]
	ds_read_b128 v[130:133], v162 offset:4640
	ds_read_b128 v[134:137], v162 offset:9248
	ds_read_b128 v[138:141], v162 offset:13856
	ds_read_b128 v[142:145], v163 offset:41504
	s_waitcnt lgkmcnt(4)
	v_mfma_f32_32x32x16_f16 v[114:129], v[158:161], v[150:153], v[114:129]
	s_waitcnt lgkmcnt(0)
	v_mfma_f32_32x32x16_f16 v[98:113], v[142:145], v[150:153], v[98:113]
	v_mfma_f32_32x32x16_f16 v[18:33], v[158:161], v[138:141], v[18:33]
	v_mfma_f32_32x32x16_f16 v[2:17], v[142:145], v[138:141], v[2:17]
	v_mfma_f32_32x32x16_f16 v[82:97], v[158:161], v[130:133], v[82:97]
	v_mfma_f32_32x32x16_f16 v[66:81], v[142:145], v[130:133], v[66:81]
	v_mfma_f32_32x32x16_f16 v[50:65], v[158:161], v[134:137], v[50:65]
	v_mfma_f32_32x32x16_f16 v[34:49], v[142:145], v[134:137], v[34:49]
	ds_read_b128 v[130:133], v162 offset:64
	ds_read_b128 v[134:137], v162 offset:4672
	ds_read_b128 v[138:141], v162 offset:9280
	ds_read_b128 v[142:145], v162 offset:13888
	ds_read_b128 v[146:149], v163 offset:36928
	ds_read_b128 v[150:153], v163 offset:41536
	s_waitcnt lgkmcnt(1)
	v_mfma_f32_32x32x16_f16 v[114:129], v[146:149], v[130:133], v[114:129]
	s_waitcnt lgkmcnt(0)
	v_mfma_f32_32x32x16_f16 v[98:113], v[150:153], v[130:133], v[98:113]
	v_mfma_f32_32x32x16_f16 v[18:33], v[146:149], v[142:145], v[18:33]
	v_mfma_f32_32x32x16_f16 v[2:17], v[150:153], v[142:145], v[2:17]
	v_mfma_f32_32x32x16_f16 v[82:97], v[146:149], v[134:137], v[82:97]
	v_mfma_f32_32x32x16_f16 v[66:81], v[150:153], v[134:137], v[66:81]
	v_mfma_f32_32x32x16_f16 v[50:65], v[146:149], v[138:141], v[50:65]
	v_mfma_f32_32x32x16_f16 v[34:49], v[150:153], v[138:141], v[34:49]
	ds_read_b128 v[130:133], v162 offset:96
	ds_read_b128 v[134:137], v162 offset:4704
	ds_read_b128 v[138:141], v162 offset:9312
	ds_read_b128 v[142:145], v162 offset:13920
	ds_read_b128 v[146:149], v163 offset:36960
	ds_read_b128 v[150:153], v163 offset:41568
	s_waitcnt lgkmcnt(0)
	s_barrier
	v_mfma_f32_32x32x16_f16 v[114:129], v[146:149], v[130:133], v[114:129]
	v_mfma_f32_32x32x16_f16 v[98:113], v[150:153], v[130:133], v[98:113]
	v_mfma_f32_32x32x16_f16 v[18:33], v[146:149], v[142:145], v[18:33]
	v_mfma_f32_32x32x16_f16 v[2:17], v[150:153], v[142:145], v[2:17]
	v_lshlrev_b32_e32 v142, 1, v174
	v_add3_u32 v162, s7, v142, v171
	v_add3_u32 v1, s8, v142, v1
	v_mfma_f32_32x32x16_f16 v[82:97], v[146:149], v[134:137], v[82:97]
	v_mfma_f32_32x32x16_f16 v[66:81], v[150:153], v[134:137], v[66:81]
	v_mfma_f32_32x32x16_f16 v[50:65], v[146:149], v[138:141], v[50:65]
	v_mfma_f32_32x32x16_f16 v[34:49], v[150:153], v[138:141], v[34:49]
	ds_read_b128 v[130:133], v162 offset:4608
	ds_read_b128 v[134:137], v162 offset:9216
	ds_read_b128 v[138:141], v162 offset:13824
	ds_read_b128 v[142:145], v1 offset:4608
	ds_read_b128 v[146:149], v162
	ds_read_b128 v[150:153], v162 offset:32
	ds_read_b128 v[154:157], v1
	ds_read_b128 v[158:161], v1 offset:32
	s_waitcnt lgkmcnt(1)
	v_mfma_f32_32x32x16_f16 v[114:129], v[154:157], v[146:149], v[114:129]
	v_mfma_f32_32x32x16_f16 v[98:113], v[142:145], v[146:149], v[98:113]
	v_mfma_f32_32x32x16_f16 v[82:97], v[154:157], v[130:133], v[82:97]
	v_mfma_f32_32x32x16_f16 v[66:81], v[142:145], v[130:133], v[66:81]
	v_mfma_f32_32x32x16_f16 v[50:65], v[154:157], v[134:137], v[50:65]
	v_mfma_f32_32x32x16_f16 v[34:49], v[142:145], v[134:137], v[34:49]
	v_mfma_f32_32x32x16_f16 v[18:33], v[154:157], v[138:141], v[18:33]
	v_mfma_f32_32x32x16_f16 v[2:17], v[142:145], v[138:141], v[2:17]
	ds_read_b128 v[130:133], v162 offset:4640
	ds_read_b128 v[134:137], v162 offset:9248
	ds_read_b128 v[138:141], v162 offset:13856
	ds_read_b128 v[142:145], v1 offset:4640
	s_waitcnt lgkmcnt(4)
	v_mfma_f32_32x32x16_f16 v[114:129], v[158:161], v[150:153], v[114:129]
	s_waitcnt lgkmcnt(0)
; DI int otid512() { int t = threadIdx.x; asm volatile("" : "+v"(t)); return t; }
; template <class Epi>
; DI void gemm256_epilogue(f16v (&acc)[4][2], int m0, int n0, Epi epi) {
;   const int tid = otid512(), lane = tid & 63, wv = tid >> 6, wm = wv >> 2, wn = wv & 3, h = lane >> 5;
; #pragma unroll
;   for (int i = 0; i < 4; ++i) {
;     const int m = m0 + wm * 128 + i * 32 + (lane & 31);
; #pragma unroll
;     for (int g = 0; g < 4; ++g) {
;       const int n = n0 + wn * 64 + 8 * g + 4 * h;
;       f4v v0 = {acc[i][0][4 * g], acc[i][0][4 * g + 1], acc[i][0][4 * g + 2], acc[i][0][4 * g + 3]};
;       f4v v1 = {acc[i][1][4 * g], acc[i][1][4 * g + 1], acc[i][1][4 * g + 2], acc[i][1][4 * g + 3]};
;       epi(m, n, v0, v1);
;     }
;   }
; }
; DI void phase_resid_gemm(const Params& p, const h16* A, int lda, const h16* W, int K, const float* xres, int bid, int nb, h16* lds) {
;     ...
;   for (int u = bid; u < 64 * 4; u += nb) {
;     const int m0 = (u >> 2) * 256, n0 = (u & 3) * 256;
;     f16v acc[4][2]; acc256_zero(acc);
;     gemm256_main<false>(A, lda, nullptr, m0, W, K, n0, K, lds, acc);
;     gemm256_epilogue(acc, m0, n0, [&](int m, int n, f4v v0, f4v v1) {
;       const f4v x0 = *(const f4v*)&xres[(size_t)m * DM + n], x1 = *(const f4v*)&xres[(size_t)m * DM + n + 32];
;       *(f4v*)&out[(size_t)m * DM + n] = ALPHA * x0 + v0;
;       *(f4v*)&out[(size_t)m * DM + n + 32] = ALPHA * x1 + v1;
;     });
;   }
	v_mfma_f32_32x32x16_f16 v[98:113], v[142:145], v[150:153], v[98:113]
	v_mfma_f32_32x32x16_f16 v[82:97], v[158:161], v[130:133], v[82:97]
	v_mfma_f32_32x32x16_f16 v[66:81], v[142:145], v[130:133], v[66:81]
	v_mfma_f32_32x32x16_f16 v[50:65], v[158:161], v[134:137], v[50:65]
	v_mfma_f32_32x32x16_f16 v[34:49], v[142:145], v[134:137], v[34:49]
	v_mfma_f32_32x32x16_f16 v[18:33], v[158:161], v[138:141], v[18:33]
	v_mfma_f32_32x32x16_f16 v[2:17], v[142:145], v[138:141], v[2:17]
	ds_read_b128 v[130:133], v162 offset:64
	ds_read_b128 v[134:137], v162 offset:4672
	ds_read_b128 v[138:141], v162 offset:9280
	ds_read_b128 v[142:145], v162 offset:13888
	ds_read_b128 v[146:149], v1 offset:64
	ds_read_b128 v[150:153], v1 offset:4672
	s_waitcnt lgkmcnt(1)
	v_mfma_f32_32x32x16_f16 v[114:129], v[146:149], v[130:133], v[114:129]
	s_waitcnt lgkmcnt(0)
	v_mfma_f32_32x32x16_f16 v[98:113], v[150:153], v[130:133], v[98:113]
	v_mfma_f32_32x32x16_f16 v[82:97], v[146:149], v[134:137], v[82:97]
	v_mfma_f32_32x32x16_f16 v[66:81], v[150:153], v[134:137], v[66:81]
	v_mfma_f32_32x32x16_f16 v[50:65], v[146:149], v[138:141], v[50:65]
	v_mfma_f32_32x32x16_f16 v[34:49], v[150:153], v[138:141], v[34:49]
	v_mfma_f32_32x32x16_f16 v[18:33], v[146:149], v[142:145], v[18:33]
	v_mfma_f32_32x32x16_f16 v[2:17], v[150:153], v[142:145], v[2:17]
	ds_read_b128 v[130:133], v162 offset:96
	ds_read_b128 v[134:137], v162 offset:4704
	ds_read_b128 v[138:141], v162 offset:9312
	ds_read_b128 v[142:145], v162 offset:13920
	ds_read_b128 v[146:149], v1 offset:96
	ds_read_b128 v[150:153], v1 offset:4704
	v_mov_b32_e32 v1, v180
	s_waitcnt lgkmcnt(0)
	s_barrier
	v_mfma_f32_32x32x16_f16 v[114:129], v[146:149], v[130:133], v[114:129]
	v_mfma_f32_32x32x16_f16 v[98:113], v[150:153], v[130:133], v[98:113]
	v_mfma_f32_32x32x16_f16 v[50:65], v[146:149], v[138:141], v[50:65]
	v_mfma_f32_32x32x16_f16 v[34:49], v[150:153], v[138:141], v[34:49]
	v_mfma_f32_32x32x16_f16 v[18:33], v[146:149], v[142:145], v[18:33]
	v_mfma_f32_32x32x16_f16 v[2:17], v[150:153], v[142:145], v[2:17]
	v_mfma_f32_32x32x16_f16 v[82:97], v[146:149], v[134:137], v[82:97]
	v_mfma_f32_32x32x16_f16 v[66:81], v[150:153], v[134:137], v[66:81]
	s_nop 15
	s_cselect_b32 s60, 1, 0
	s_barrier
	v_readfirstlane_b32 s66, v180
	s_mov_b32 s69, s5
	s_mov_b32 s65, s6
	s_lshr_b32 s66, s66, 6
	s_and_b32 s67, s66, 3
	s_lshr_b32 s68, s66, 2
	s_lshl_b32 s70, s67, 6
	s_add_i32 s70, s70, s69
	s_lshl_b32 s71, s68, 7
	s_add_i32 s71, s71, s65
	s_mul_i32 s72, s66, 0x4400
	s_add_i32 s72, s72, 16
	v_and_b32_e32 v136, 63, v180
	v_and_b32_e32 v137, 31, v136
	v_lshrrev_b32_e32 v138, 5, v136
	v_mul_u32_u24_e32 v130, 0x110, v137
	v_lshl_add_u32 v130, v138, 4, v130
	v_add_u32_e32 v130, s72, v130
	v_lshrrev_b32_e32 v137, 4, v136
	v_and_b32_e32 v138, 15, v136
	v_mul_u32_u24_e32 v131, 0x110, v137
	v_lshl_add_u32 v131, v138, 4, v131
	v_add_u32_e32 v131, s72, v131
	v_add_u32_e32 v137, s71, v137
	v_lshl_add_u32 v138, v138, 2, s70
	v_lshlrev_b32_e32 v138, 2, v138
	v_mov_b32_e32 v139, v0
	s_mov_b32 s73, 0x1000
	v_mov_b64_e32 v[132:133], s[2:3]
	v_mad_u64_u32 v[132:133], s[74:75], v137, s73, v[132:133]
	v_lshl_add_u64 v[132:133], v[132:133], 0, v[138:139]
	v_mov_b64_e32 v[134:135], s[18:19]
	v_mad_u64_u32 v[134:135], s[74:75], v137, s73, v[134:135]
	v_lshl_add_u64 v[134:135], v[134:135], 0, v[138:139]
	s_mov_b32 s76, 0x4000
	s_mov_b32 s77, 0
	ds_write_b128 v130, v[114:117]
	ds_write_b128 v130, v[118:121] offset:32
	ds_write_b128 v130, v[122:125] offset:64
	ds_write_b128 v130, v[126:129] offset:96
	ds_write_b128 v130, v[98:101] offset:128
	ds_write_b128 v130, v[102:105] offset:160
	ds_write_b128 v130, v[106:109] offset:192
	ds_write_b128 v130, v[110:113] offset:224
	ds_write_b128 v130, v[82:85] offset:8704
	ds_write_b128 v130, v[86:89] offset:8736
	ds_write_b128 v130, v[90:93] offset:8768
	ds_write_b128 v130, v[94:97] offset:8800
	ds_write_b128 v130, v[66:69] offset:8832
	ds_write_b128 v130, v[70:73] offset:8864
	ds_write_b128 v130, v[74:77] offset:8896
	ds_write_b128 v130, v[78:81] offset:8928
	global_load_dwordx4 v[224:227], v[132:133], off
	v_lshl_add_u64 v[132:133], v[132:133], 0, s[76:77]
	global_load_dwordx4 v[228:231], v[132:133], off
	v_lshl_add_u64 v[132:133], v[132:133], 0, s[76:77]
	global_load_dwordx4 v[232:235], v[132:133], off
	v_lshl_add_u64 v[132:133], v[132:133], 0, s[76:77]
	global_load_dwordx4 v[236:239], v[132:133], off
	v_lshl_add_u64 v[132:133], v[132:133], 0, s[76:77]
	global_load_dwordx4 v[240:243], v[132:133], off
	v_lshl_add_u64 v[132:133], v[132:133], 0, s[76:77]
	global_load_dwordx4 v[244:247], v[132:133], off
	v_lshl_add_u64 v[132:133], v[132:133], 0, s[76:77]
	global_load_dwordx4 v[176:179], v[132:133], off
	v_lshl_add_u64 v[132:133], v[132:133], 0, s[76:77]
	global_load_dwordx4 v[200:203], v[132:133], off
	v_lshl_add_u64 v[132:133], v[132:133], 0, s[76:77]
	ds_read_b128 v[140:143], v131
	ds_read_b128 v[144:147], v131 offset:1088
	ds_read_b128 v[148:151], v131 offset:2176
	ds_read_b128 v[152:155], v131 offset:3264
	ds_read_b128 v[156:159], v131 offset:4352
	ds_read_b128 v[160:163], v131 offset:5440
	ds_read_b128 v[216:219], v131 offset:6528
	ds_read_b128 v[220:223], v131 offset:7616
	s_waitcnt vmcnt(7) lgkmcnt(7)
	v_pk_fma_f32 v[140:141], v[224:225], s[10:11], v[140:141] op_sel_hi:[1,0,1]
	v_pk_fma_f32 v[142:143], v[226:227], s[10:11], v[142:143] op_sel_hi:[1,0,1]
	global_store_dwordx4 v[134:135], v[140:143], off
	v_lshl_add_u64 v[134:135], v[134:135], 0, s[76:77]
	s_waitcnt vmcnt(7) lgkmcnt(6)
	v_pk_fma_f32 v[144:145], v[228:229], s[10:11], v[144:145] op_sel_hi:[1,0,1]
	v_pk_fma_f32 v[146:147], v[230:231], s[10:11], v[146:147] op_sel_hi:[1,0,1]
	global_store_dwordx4 v[134:135], v[144:147], off
	v_lshl_add_u64 v[134:135], v[134:135], 0, s[76:77]
	s_waitcnt vmcnt(7) lgkmcnt(5)
; DI int otid512() { int t = threadIdx.x; asm volatile("" : "+v"(t)); return t; }
; template <class Epi>
; DI void gemm256_epilogue(f16v (&acc)[4][2], int m0, int n0, Epi epi) {
;   const int tid = otid512(), lane = tid & 63, wv = tid >> 6, wm = wv >> 2, wn = wv & 3, h = lane >> 5;
; #pragma unroll
;   for (int i = 0; i < 4; ++i) {
;     const int m = m0 + wm * 128 + i * 32 + (lane & 31);
; #pragma unroll
;     for (int g = 0; g < 4; ++g) {
;       const int n = n0 + wn * 64 + 8 * g + 4 * h;
;       f4v v0 = {acc[i][0][4 * g], acc[i][0][4 * g + 1], acc[i][0][4 * g + 2], acc[i][0][4 * g + 3]};
;       f4v v1 = {acc[i][1][4 * g], acc[i][1][4 * g + 1], acc[i][1][4 * g + 2], acc[i][1][4 * g + 3]};
;       epi(m, n, v0, v1);
;     }
;   }
; }
; DI void phase_resid_gemm(const Params& p, const h16* A, int lda, const h16* W, int K, const float* xres, int bid, int nb, h16* lds) {
;     ...
;     gemm256_epilogue(acc, m0, n0, [&](int m, int n, f4v v0, f4v v1) {
;       const f4v x0 = *(const f4v*)&xres[(size_t)m * DM + n], x1 = *(const f4v*)&xres[(size_t)m * DM + n + 32];
;       *(f4v*)&out[(size_t)m * DM + n] = ALPHA * x0 + v0;
;       *(f4v*)&out[(size_t)m * DM + n + 32] = ALPHA * x1 + v1;
;     });
	v_pk_fma_f32 v[148:149], v[232:233], s[10:11], v[148:149] op_sel_hi:[1,0,1]
	v_pk_fma_f32 v[150:151], v[234:235], s[10:11], v[150:151] op_sel_hi:[1,0,1]
	global_store_dwordx4 v[134:135], v[148:151], off
	v_lshl_add_u64 v[134:135], v[134:135], 0, s[76:77]
	s_waitcnt vmcnt(7) lgkmcnt(4)
	v_pk_fma_f32 v[152:153], v[236:237], s[10:11], v[152:153] op_sel_hi:[1,0,1]
	v_pk_fma_f32 v[154:155], v[238:239], s[10:11], v[154:155] op_sel_hi:[1,0,1]
	global_store_dwordx4 v[134:135], v[152:155], off
	v_lshl_add_u64 v[134:135], v[134:135], 0, s[76:77]
	s_waitcnt vmcnt(7) lgkmcnt(3)
	v_pk_fma_f32 v[156:157], v[240:241], s[10:11], v[156:157] op_sel_hi:[1,0,1]
	v_pk_fma_f32 v[158:159], v[242:243], s[10:11], v[158:159] op_sel_hi:[1,0,1]
	global_store_dwordx4 v[134:135], v[156:159], off
	v_lshl_add_u64 v[134:135], v[134:135], 0, s[76:77]
	s_waitcnt vmcnt(7) lgkmcnt(2)
	v_pk_fma_f32 v[160:161], v[244:245], s[10:11], v[160:161] op_sel_hi:[1,0,1]
	v_pk_fma_f32 v[162:163], v[246:247], s[10:11], v[162:163] op_sel_hi:[1,0,1]
	global_store_dwordx4 v[134:135], v[160:163], off
	v_lshl_add_u64 v[134:135], v[134:135], 0, s[76:77]
	s_waitcnt vmcnt(7) lgkmcnt(1)
	v_pk_fma_f32 v[216:217], v[176:177], s[10:11], v[216:217] op_sel_hi:[1,0,1]
	v_pk_fma_f32 v[218:219], v[178:179], s[10:11], v[218:219] op_sel_hi:[1,0,1]
	global_store_dwordx4 v[134:135], v[216:219], off
	v_lshl_add_u64 v[134:135], v[134:135], 0, s[76:77]
	s_waitcnt vmcnt(7) lgkmcnt(0)
	v_pk_fma_f32 v[220:221], v[200:201], s[10:11], v[220:221] op_sel_hi:[1,0,1]
	v_pk_fma_f32 v[222:223], v[202:203], s[10:11], v[222:223] op_sel_hi:[1,0,1]
	global_store_dwordx4 v[134:135], v[220:223], off
	v_lshl_add_u64 v[134:135], v[134:135], 0, s[76:77]
	s_nop 1
	global_load_dwordx4 v[224:227], v[132:133], off
	v_lshl_add_u64 v[132:133], v[132:133], 0, s[76:77]
	global_load_dwordx4 v[228:231], v[132:133], off
	v_lshl_add_u64 v[132:133], v[132:133], 0, s[76:77]
	global_load_dwordx4 v[232:235], v[132:133], off
	v_lshl_add_u64 v[132:133], v[132:133], 0, s[76:77]
	global_load_dwordx4 v[236:239], v[132:133], off
	v_lshl_add_u64 v[132:133], v[132:133], 0, s[76:77]
	global_load_dwordx4 v[240:243], v[132:133], off
	v_lshl_add_u64 v[132:133], v[132:133], 0, s[76:77]
	global_load_dwordx4 v[244:247], v[132:133], off
	v_lshl_add_u64 v[132:133], v[132:133], 0, s[76:77]
	global_load_dwordx4 v[176:179], v[132:133], off
	v_lshl_add_u64 v[132:133], v[132:133], 0, s[76:77]
	global_load_dwordx4 v[200:203], v[132:133], off
	v_lshl_add_u64 v[132:133], v[132:133], 0, s[76:77]
	ds_read_b128 v[140:143], v131 offset:8704
	ds_read_b128 v[144:147], v131 offset:9792
	ds_read_b128 v[148:151], v131 offset:10880
	ds_read_b128 v[152:155], v131 offset:11968
	ds_read_b128 v[156:159], v131 offset:13056
	ds_read_b128 v[160:163], v131 offset:14144
	ds_read_b128 v[216:219], v131 offset:15232
	ds_read_b128 v[220:223], v131 offset:16320
	s_waitcnt vmcnt(7) lgkmcnt(7)
	v_pk_fma_f32 v[140:141], v[224:225], s[10:11], v[140:141] op_sel_hi:[1,0,1]
	v_pk_fma_f32 v[142:143], v[226:227], s[10:11], v[142:143] op_sel_hi:[1,0,1]
	global_store_dwordx4 v[134:135], v[140:143], off
	v_lshl_add_u64 v[134:135], v[134:135], 0, s[76:77]
	s_waitcnt vmcnt(7) lgkmcnt(6)
	v_pk_fma_f32 v[144:145], v[228:229], s[10:11], v[144:145] op_sel_hi:[1,0,1]
	v_pk_fma_f32 v[146:147], v[230:231], s[10:11], v[146:147] op_sel_hi:[1,0,1]
	global_store_dwordx4 v[134:135], v[144:147], off
	v_lshl_add_u64 v[134:135], v[134:135], 0, s[76:77]
	s_waitcnt vmcnt(7) lgkmcnt(5)
	v_pk_fma_f32 v[148:149], v[232:233], s[10:11], v[148:149] op_sel_hi:[1,0,1]
	v_pk_fma_f32 v[150:151], v[234:235], s[10:11], v[150:151] op_sel_hi:[1,0,1]
	global_store_dwordx4 v[134:135], v[148:151], off
	v_lshl_add_u64 v[134:135], v[134:135], 0, s[76:77]
	s_waitcnt vmcnt(7) lgkmcnt(4)
	v_pk_fma_f32 v[152:153], v[236:237], s[10:11], v[152:153] op_sel_hi:[1,0,1]
	v_pk_fma_f32 v[154:155], v[238:239], s[10:11], v[154:155] op_sel_hi:[1,0,1]
	global_store_dwordx4 v[134:135], v[152:155], off
	v_lshl_add_u64 v[134:135], v[134:135], 0, s[76:77]
	s_waitcnt vmcnt(7) lgkmcnt(3)
	v_pk_fma_f32 v[156:157], v[240:241], s[10:11], v[156:157] op_sel_hi:[1,0,1]
	v_pk_fma_f32 v[158:159], v[242:243], s[10:11], v[158:159] op_sel_hi:[1,0,1]
	global_store_dwordx4 v[134:135], v[156:159], off
	v_lshl_add_u64 v[134:135], v[134:135], 0, s[76:77]
	s_waitcnt vmcnt(7) lgkmcnt(2)
	v_pk_fma_f32 v[160:161], v[244:245], s[10:11], v[160:161] op_sel_hi:[1,0,1]
	v_pk_fma_f32 v[162:163], v[246:247], s[10:11], v[162:163] op_sel_hi:[1,0,1]
	global_store_dwordx4 v[134:135], v[160:163], off
	v_lshl_add_u64 v[134:135], v[134:135], 0, s[76:77]
	s_waitcnt vmcnt(7) lgkmcnt(1)
	v_pk_fma_f32 v[216:217], v[176:177], s[10:11], v[216:217] op_sel_hi:[1,0,1]
	v_pk_fma_f32 v[218:219], v[178:179], s[10:11], v[218:219] op_sel_hi:[1,0,1]
	global_store_dwordx4 v[134:135], v[216:219], off
	v_lshl_add_u64 v[134:135], v[134:135], 0, s[76:77]
	s_waitcnt vmcnt(7) lgkmcnt(0)
; DI int otid512() { int t = threadIdx.x; asm volatile("" : "+v"(t)); return t; }
; template <class Epi>
; DI void gemm256_epilogue(f16v (&acc)[4][2], int m0, int n0, Epi epi) {
;   const int tid = otid512(), lane = tid & 63, wv = tid >> 6, wm = wv >> 2, wn = wv & 3, h = lane >> 5;
; #pragma unroll
;   for (int i = 0; i < 4; ++i) {
;     const int m = m0 + wm * 128 + i * 32 + (lane & 31);
; #pragma unroll
;     for (int g = 0; g < 4; ++g) {
;       const int n = n0 + wn * 64 + 8 * g + 4 * h;
;       f4v v0 = {acc[i][0][4 * g], acc[i][0][4 * g + 1], acc[i][0][4 * g + 2], acc[i][0][4 * g + 3]};
;       f4v v1 = {acc[i][1][4 * g], acc[i][1][4 * g + 1], acc[i][1][4 * g + 2], acc[i][1][4 * g + 3]};
;       epi(m, n, v0, v1);
;     }
;   }
; }
; DI void phase_resid_gemm(const Params& p, const h16* A, int lda, const h16* W, int K, const float* xres, int bid, int nb, h16* lds) {
;     ...
;     gemm256_epilogue(acc, m0, n0, [&](int m, int n, f4v v0, f4v v1) {
;       const f4v x0 = *(const f4v*)&xres[(size_t)m * DM + n], x1 = *(const f4v*)&xres[(size_t)m * DM + n + 32];
;       *(f4v*)&out[(size_t)m * DM + n] = ALPHA * x0 + v0;
;       *(f4v*)&out[(size_t)m * DM + n + 32] = ALPHA * x1 + v1;
;     });
	v_pk_fma_f32 v[220:221], v[200:201], s[10:11], v[220:221] op_sel_hi:[1,0,1]
	v_pk_fma_f32 v[222:223], v[202:203], s[10:11], v[222:223] op_sel_hi:[1,0,1]
	global_store_dwordx4 v[134:135], v[220:223], off
	v_lshl_add_u64 v[134:135], v[134:135], 0, s[76:77]
	s_nop 1
	ds_write_b128 v130, v[50:53]
	ds_write_b128 v130, v[54:57] offset:32
	ds_write_b128 v130, v[58:61] offset:64
	ds_write_b128 v130, v[62:65] offset:96
	ds_write_b128 v130, v[34:37] offset:128
	ds_write_b128 v130, v[38:41] offset:160
	ds_write_b128 v130, v[42:45] offset:192
	ds_write_b128 v130, v[46:49] offset:224
	ds_write_b128 v130, v[18:21] offset:8704
	ds_write_b128 v130, v[22:25] offset:8736
	ds_write_b128 v130, v[26:29] offset:8768
	ds_write_b128 v130, v[30:33] offset:8800
	ds_write_b128 v130, v[2:5] offset:8832
	ds_write_b128 v130, v[6:9] offset:8864
	ds_write_b128 v130, v[10:13] offset:8896
	ds_write_b128 v130, v[14:17] offset:8928
	global_load_dwordx4 v[224:227], v[132:133], off
	v_lshl_add_u64 v[132:133], v[132:133], 0, s[76:77]
	global_load_dwordx4 v[228:231], v[132:133], off
	v_lshl_add_u64 v[132:133], v[132:133], 0, s[76:77]
	global_load_dwordx4 v[232:235], v[132:133], off
	v_lshl_add_u64 v[132:133], v[132:133], 0, s[76:77]
	global_load_dwordx4 v[236:239], v[132:133], off
	v_lshl_add_u64 v[132:133], v[132:133], 0, s[76:77]
	global_load_dwordx4 v[240:243], v[132:133], off
	v_lshl_add_u64 v[132:133], v[132:133], 0, s[76:77]
	global_load_dwordx4 v[244:247], v[132:133], off
	v_lshl_add_u64 v[132:133], v[132:133], 0, s[76:77]
	global_load_dwordx4 v[176:179], v[132:133], off
	v_lshl_add_u64 v[132:133], v[132:133], 0, s[76:77]
	global_load_dwordx4 v[200:203], v[132:133], off
	v_lshl_add_u64 v[132:133], v[132:133], 0, s[76:77]
	ds_read_b128 v[140:143], v131
	ds_read_b128 v[144:147], v131 offset:1088
	ds_read_b128 v[148:151], v131 offset:2176
	ds_read_b128 v[152:155], v131 offset:3264
	ds_read_b128 v[156:159], v131 offset:4352
	ds_read_b128 v[160:163], v131 offset:5440
	ds_read_b128 v[216:219], v131 offset:6528
	ds_read_b128 v[220:223], v131 offset:7616
	s_waitcnt vmcnt(7) lgkmcnt(7)
	v_pk_fma_f32 v[140:141], v[224:225], s[10:11], v[140:141] op_sel_hi:[1,0,1]
	v_pk_fma_f32 v[142:143], v[226:227], s[10:11], v[142:143] op_sel_hi:[1,0,1]
	global_store_dwordx4 v[134:135], v[140:143], off
	v_lshl_add_u64 v[134:135], v[134:135], 0, s[76:77]
	s_waitcnt vmcnt(7) lgkmcnt(6)
	v_pk_fma_f32 v[144:145], v[228:229], s[10:11], v[144:145] op_sel_hi:[1,0,1]
	v_pk_fma_f32 v[146:147], v[230:231], s[10:11], v[146:147] op_sel_hi:[1,0,1]
	global_store_dwordx4 v[134:135], v[144:147], off
	v_lshl_add_u64 v[134:135], v[134:135], 0, s[76:77]
	s_waitcnt vmcnt(7) lgkmcnt(5)
	v_pk_fma_f32 v[148:149], v[232:233], s[10:11], v[148:149] op_sel_hi:[1,0,1]
	v_pk_fma_f32 v[150:151], v[234:235], s[10:11], v[150:151] op_sel_hi:[1,0,1]
	global_store_dwordx4 v[134:135], v[148:151], off
	v_lshl_add_u64 v[134:135], v[134:135], 0, s[76:77]
	s_waitcnt vmcnt(7) lgkmcnt(4)
	v_pk_fma_f32 v[152:153], v[236:237], s[10:11], v[152:153] op_sel_hi:[1,0,1]
	v_pk_fma_f32 v[154:155], v[238:239], s[10:11], v[154:155] op_sel_hi:[1,0,1]
	global_store_dwordx4 v[134:135], v[152:155], off
	v_lshl_add_u64 v[134:135], v[134:135], 0, s[76:77]
	s_waitcnt vmcnt(7) lgkmcnt(3)
	v_pk_fma_f32 v[156:157], v[240:241], s[10:11], v[156:157] op_sel_hi:[1,0,1]
	v_pk_fma_f32 v[158:159], v[242:243], s[10:11], v[158:159] op_sel_hi:[1,0,1]
	global_store_dwordx4 v[134:135], v[156:159], off
	v_lshl_add_u64 v[134:135], v[134:135], 0, s[76:77]
	s_waitcnt vmcnt(7) lgkmcnt(2)
	v_pk_fma_f32 v[160:161], v[244:245], s[10:11], v[160:161] op_sel_hi:[1,0,1]
	v_pk_fma_f32 v[162:163], v[246:247], s[10:11], v[162:163] op_sel_hi:[1,0,1]
	global_store_dwordx4 v[134:135], v[160:163], off
	v_lshl_add_u64 v[134:135], v[134:135], 0, s[76:77]
	s_waitcnt vmcnt(7) lgkmcnt(1)
; DI int otid512() { int t = threadIdx.x; asm volatile("" : "+v"(t)); return t; }
; template <class Epi>
; DI void gemm256_epilogue(f16v (&acc)[4][2], int m0, int n0, Epi epi) {
;   const int tid = otid512(), lane = tid & 63, wv = tid >> 6, wm = wv >> 2, wn = wv & 3, h = lane >> 5;
; #pragma unroll
;   for (int i = 0; i < 4; ++i) {
;     const int m = m0 + wm * 128 + i * 32 + (lane & 31);
; #pragma unroll
;     for (int g = 0; g < 4; ++g) {
;       const int n = n0 + wn * 64 + 8 * g + 4 * h;
;       f4v v0 = {acc[i][0][4 * g], acc[i][0][4 * g + 1], acc[i][0][4 * g + 2], acc[i][0][4 * g + 3]};
;       f4v v1 = {acc[i][1][4 * g], acc[i][1][4 * g + 1], acc[i][1][4 * g + 2], acc[i][1][4 * g + 3]};
;       epi(m, n, v0, v1);
;     }
;   }
; }
; DI void phase_resid_gemm(const Params& p, const h16* A, int lda, const h16* W, int K, const float* xres, int bid, int nb, h16* lds) {
;     ...
;     gemm256_epilogue(acc, m0, n0, [&](int m, int n, f4v v0, f4v v1) {
;       const f4v x0 = *(const f4v*)&xres[(size_t)m * DM + n], x1 = *(const f4v*)&xres[(size_t)m * DM + n + 32];
;       *(f4v*)&out[(size_t)m * DM + n] = ALPHA * x0 + v0;
;       *(f4v*)&out[(size_t)m * DM + n + 32] = ALPHA * x1 + v1;
;     });
	v_pk_fma_f32 v[216:217], v[176:177], s[10:11], v[216:217] op_sel_hi:[1,0,1]
	v_pk_fma_f32 v[218:219], v[178:179], s[10:11], v[218:219] op_sel_hi:[1,0,1]
	global_store_dwordx4 v[134:135], v[216:219], off
	v_lshl_add_u64 v[134:135], v[134:135], 0, s[76:77]
	s_waitcnt vmcnt(7) lgkmcnt(0)
	v_pk_fma_f32 v[220:221], v[200:201], s[10:11], v[220:221] op_sel_hi:[1,0,1]
	v_pk_fma_f32 v[222:223], v[202:203], s[10:11], v[222:223] op_sel_hi:[1,0,1]
	global_store_dwordx4 v[134:135], v[220:223], off
	v_lshl_add_u64 v[134:135], v[134:135], 0, s[76:77]
	s_nop 1
	global_load_dwordx4 v[224:227], v[132:133], off
	v_lshl_add_u64 v[132:133], v[132:133], 0, s[76:77]
	global_load_dwordx4 v[228:231], v[132:133], off
	v_lshl_add_u64 v[132:133], v[132:133], 0, s[76:77]
	global_load_dwordx4 v[232:235], v[132:133], off
	v_lshl_add_u64 v[132:133], v[132:133], 0, s[76:77]
	global_load_dwordx4 v[236:239], v[132:133], off
	v_lshl_add_u64 v[132:133], v[132:133], 0, s[76:77]
	global_load_dwordx4 v[240:243], v[132:133], off
	v_lshl_add_u64 v[132:133], v[132:133], 0, s[76:77]
	global_load_dwordx4 v[244:247], v[132:133], off
	v_lshl_add_u64 v[132:133], v[132:133], 0, s[76:77]
	global_load_dwordx4 v[176:179], v[132:133], off
	v_lshl_add_u64 v[132:133], v[132:133], 0, s[76:77]
	global_load_dwordx4 v[200:203], v[132:133], off
	v_lshl_add_u64 v[132:133], v[132:133], 0, s[76:77]
	ds_read_b128 v[140:143], v131 offset:8704
	ds_read_b128 v[144:147], v131 offset:9792
	ds_read_b128 v[148:151], v131 offset:10880
	ds_read_b128 v[152:155], v131 offset:11968
	ds_read_b128 v[156:159], v131 offset:13056
	ds_read_b128 v[160:163], v131 offset:14144
	ds_read_b128 v[216:219], v131 offset:15232
	ds_read_b128 v[220:223], v131 offset:16320
	s_waitcnt vmcnt(7) lgkmcnt(7)
	v_pk_fma_f32 v[140:141], v[224:225], s[10:11], v[140:141] op_sel_hi:[1,0,1]
	v_pk_fma_f32 v[142:143], v[226:227], s[10:11], v[142:143] op_sel_hi:[1,0,1]
	global_store_dwordx4 v[134:135], v[140:143], off
	v_lshl_add_u64 v[134:135], v[134:135], 0, s[76:77]
	s_waitcnt vmcnt(7) lgkmcnt(6)
	v_pk_fma_f32 v[144:145], v[228:229], s[10:11], v[144:145] op_sel_hi:[1,0,1]
	v_pk_fma_f32 v[146:147], v[230:231], s[10:11], v[146:147] op_sel_hi:[1,0,1]
	global_store_dwordx4 v[134:135], v[144:147], off
	v_lshl_add_u64 v[134:135], v[134:135], 0, s[76:77]
	s_waitcnt vmcnt(7) lgkmcnt(5)
	v_pk_fma_f32 v[148:149], v[232:233], s[10:11], v[148:149] op_sel_hi:[1,0,1]
	v_pk_fma_f32 v[150:151], v[234:235], s[10:11], v[150:151] op_sel_hi:[1,0,1]
	global_store_dwordx4 v[134:135], v[148:151], off
	v_lshl_add_u64 v[134:135], v[134:135], 0, s[76:77]
	s_waitcnt vmcnt(7) lgkmcnt(4)
	v_pk_fma_f32 v[152:153], v[236:237], s[10:11], v[152:153] op_sel_hi:[1,0,1]
	v_pk_fma_f32 v[154:155], v[238:239], s[10:11], v[154:155] op_sel_hi:[1,0,1]
	global_store_dwordx4 v[134:135], v[152:155], off
	v_lshl_add_u64 v[134:135], v[134:135], 0, s[76:77]
	s_waitcnt vmcnt(7) lgkmcnt(3)
	v_pk_fma_f32 v[156:157], v[240:241], s[10:11], v[156:157] op_sel_hi:[1,0,1]
	v_pk_fma_f32 v[158:159], v[242:243], s[10:11], v[158:159] op_sel_hi:[1,0,1]
	global_store_dwordx4 v[134:135], v[156:159], off
	v_lshl_add_u64 v[134:135], v[134:135], 0, s[76:77]
	s_waitcnt vmcnt(7) lgkmcnt(2)
	v_pk_fma_f32 v[160:161], v[244:245], s[10:11], v[160:161] op_sel_hi:[1,0,1]
	v_pk_fma_f32 v[162:163], v[246:247], s[10:11], v[162:163] op_sel_hi:[1,0,1]
	global_store_dwordx4 v[134:135], v[160:163], off
	v_lshl_add_u64 v[134:135], v[134:135], 0, s[76:77]
	s_waitcnt vmcnt(7) lgkmcnt(1)
	v_pk_fma_f32 v[216:217], v[176:177], s[10:11], v[216:217] op_sel_hi:[1,0,1]
	v_pk_fma_f32 v[218:219], v[178:179], s[10:11], v[218:219] op_sel_hi:[1,0,1]
	global_store_dwordx4 v[134:135], v[216:219], off
	v_lshl_add_u64 v[134:135], v[134:135], 0, s[76:77]
	s_waitcnt vmcnt(7) lgkmcnt(0)
	v_pk_fma_f32 v[220:221], v[200:201], s[10:11], v[220:221] op_sel_hi:[1,0,1]
	v_pk_fma_f32 v[222:223], v[202:203], s[10:11], v[222:223] op_sel_hi:[1,0,1]
	global_store_dwordx4 v[134:135], v[220:223], off
	v_lshl_add_u64 v[134:135], v[134:135], 0, s[76:77]
	s_nop 1
	s_cmp_eq_u32 s60, 1
	s_cbranch_scc0 .LBB0_1354

; DI f16v mfma32(h8v a, h8v b, f16v c) { return __builtin_amdgcn_mfma_f32_32x32x16_f16(a, b, c, 0, 0, 0); }
; template <bool GATHER>
; DI void gemm256_main(const h16* __restrict__ A, int lda, const int* __restrict__ idx, int m0,
;                      const h16* __restrict__ B, int ldb, int n0, int K, h16* lds, f16v (&acc)[4][2]) {
;     ...
;   for (int kt = 0; kt < nk; ++kt) {
;     const h16* As = lds + (kt & 1) * (512 * LDH);
;     const h16* Bs = As + 256 * LDH;
;     h16* Wn = lds + ((kt & 1) ^ 1) * (512 * LDH);
;     if (kt + 1 < nk) {
; #pragma unroll
;       for (int i = 0; i < 4; ++i) { *(u4v*)&Wn[lr * LDH + lc + 8 * i] = ra[i]; *(u4v*)&Wn[(256 + lr) * LDH + lc + 8 * i] = rb[i]; }
;     }
;     if (kt + 2 < nk) {
; #pragma unroll
;       for (int i = 0; i < 4; ++i) { ra[i] = *(const u4v*)(AP_ + 8 * i); rb[i] = *(const u4v*)(BP_ + 8 * i); }
;       ao += 64; bo += 64;
;     }
; #pragma unroll
;     for (int ks = 0; ks < 4; ++ks) {
;       h8v af[4], bf[2];
; #pragma unroll
;       for (int i = 0; i < 4; ++i) af[i] = *(const h8v*)&As[(wm * 128 + i * 32 + (lane & 31)) * LDH + ks * 16 + 8 * (lane >> 5)];
; #pragma unroll
;       for (int j = 0; j < 2; ++j) bf[j] = *(const h8v*)&Bs[(wn * 64 + j * 32 + (lane & 31)) * LDH + ks * 16 + 8 * (lane >> 5)];
; #pragma unroll
;       for (int i = 0; i < 4; ++i)
; #pragma unroll
;         for (int j = 0; j < 2; ++j) acc[i][j] = mfma32(bf[j], af[i], acc[i][j]);
;     }
;     __syncthreads();
;   }
.LBB0_1677:
	s_and_b32 s6, s5, 1
	s_mul_i32 s7, s6, 0x12000
	s_xor_b32 s6, s6, 1
	s_mul_i32 s6, s6, 0x12000
	v_add_u32_e32 v163, s7, v175
	v_add_u32_e32 v165, s6, v176
	v_add_u32_e32 v177, v163, v171
	v_add_u32_e32 v163, v163, v1
	s_waitcnt vmcnt(4)
	ds_write_b128 v165, v[150:153]
	s_waitcnt vmcnt(0)
	ds_write_b128 v165, v[158:161] offset:36864
	ds_write_b128 v165, v[142:145] offset:16
	ds_write_b128 v165, v[154:157] offset:36880
	ds_write_b128 v165, v[134:137] offset:32
	ds_write_b128 v165, v[146:149] offset:36896
	ds_write_b128 v165, v[130:133] offset:48
	ds_write_b128 v165, v[138:141] offset:36912
	ds_read_b128 v[130:133], v163 offset:36864
	ds_read_b128 v[134:137], v177
	ds_read_b128 v[138:141], v177 offset:32
	ds_read_b128 v[142:145], v163 offset:36896
	ds_read_b128 v[146:149], v163 offset:41472
	ds_read_b128 v[150:153], v163 offset:41504
	s_waitcnt lgkmcnt(4)
	v_mfma_f32_32x32x16_f16 v[114:129], v[130:133], v[134:137], v[114:129]
	v_mov_b32_e32 v165, v0
	s_add_i32 s5, s5, 1
	s_cmp_eq_u32 s5, 42
	s_waitcnt lgkmcnt(1)
	v_mfma_f32_32x32x16_f16 v[98:113], v[146:149], v[134:137], v[98:113]
	ds_read_b128 v[134:137], v177 offset:4608
	ds_read_b128 v[154:157], v177 offset:4640
	s_waitcnt lgkmcnt(1)
	v_mfma_f32_32x32x16_f16 v[82:97], v[130:133], v[134:137], v[82:97]
	v_mfma_f32_32x32x16_f16 v[66:81], v[146:149], v[134:137], v[66:81]
	ds_read_b128 v[134:137], v177 offset:9216
	ds_read_b128 v[158:161], v177 offset:9248
	s_waitcnt lgkmcnt(1)
	v_mfma_f32_32x32x16_f16 v[50:65], v[130:133], v[134:137], v[50:65]
	v_mfma_f32_32x32x16_f16 v[34:49], v[146:149], v[134:137], v[34:49]
	ds_read_b128 v[134:137], v177 offset:13824
	ds_read_b128 v[200:203], v177 offset:13856
	s_waitcnt lgkmcnt(1)
	v_mfma_f32_32x32x16_f16 v[18:33], v[130:133], v[134:137], v[18:33]
	v_mfma_f32_32x32x16_f16 v[2:17], v[146:149], v[134:137], v[2:17]
	v_mfma_f32_32x32x16_f16 v[114:129], v[142:145], v[138:141], v[114:129]
	v_mfma_f32_32x32x16_f16 v[98:113], v[150:153], v[138:141], v[98:113]
	v_mfma_f32_32x32x16_f16 v[82:97], v[142:145], v[154:157], v[82:97]
	v_mfma_f32_32x32x16_f16 v[66:81], v[150:153], v[154:157], v[66:81]
	v_mfma_f32_32x32x16_f16 v[50:65], v[142:145], v[158:161], v[50:65]
	v_mfma_f32_32x32x16_f16 v[34:49], v[150:153], v[158:161], v[34:49]
	ds_read_b128 v[130:133], v163 offset:36928
	ds_read_b128 v[134:137], v177 offset:64
	ds_read_b128 v[138:141], v177 offset:96
	ds_read_b128 v[158:161], v163 offset:36960
	s_waitcnt lgkmcnt(4)
	v_mfma_f32_32x32x16_f16 v[18:33], v[142:145], v[200:203], v[18:33]
	v_mfma_f32_32x32x16_f16 v[2:17], v[150:153], v[200:203], v[2:17]
	ds_read_b128 v[142:145], v163 offset:41536
	ds_read_b128 v[200:203], v163 offset:41568
	v_mov_b32_e32 v163, v0
	v_lshl_add_u64 v[178:179], v[162:163], 1, s[8:9]
	v_add_u32_e32 v162, 64, v162
	s_waitcnt lgkmcnt(4)
	v_mfma_f32_32x32x16_f16 v[114:129], v[130:133], v[134:137], v[114:129]
	s_waitcnt lgkmcnt(1)
	v_mfma_f32_32x32x16_f16 v[98:113], v[142:145], v[134:137], v[98:113]
	ds_read_b128 v[134:137], v177 offset:4672
	ds_read_b128 v[146:149], v177 offset:4704
	s_waitcnt lgkmcnt(1)
	v_mfma_f32_32x32x16_f16 v[82:97], v[130:133], v[134:137], v[82:97]
	v_mfma_f32_32x32x16_f16 v[66:81], v[142:145], v[134:137], v[66:81]
	ds_read_b128 v[134:137], v177 offset:9280
	ds_read_b128 v[150:153], v177 offset:9312
	s_waitcnt lgkmcnt(1)
	v_mfma_f32_32x32x16_f16 v[50:65], v[130:133], v[134:137], v[50:65]
	v_mfma_f32_32x32x16_f16 v[34:49], v[142:145], v[134:137], v[34:49]
	ds_read_b128 v[134:137], v177 offset:13888
	ds_read_b128 v[216:219], v177 offset:13920
	s_waitcnt lgkmcnt(1)
	v_mfma_f32_32x32x16_f16 v[18:33], v[130:133], v[134:137], v[18:33]
	v_mfma_f32_32x32x16_f16 v[114:129], v[158:161], v[138:141], v[114:129]
	v_mfma_f32_32x32x16_f16 v[98:113], v[200:203], v[138:141], v[98:113]
	v_lshl_add_u64 v[138:139], v[164:165], 1, s[0:1]
	v_add_u32_e32 v164, 64, v164
	v_mfma_f32_32x32x16_f16 v[2:17], v[142:145], v[134:137], v[2:17]
	v_mfma_f32_32x32x16_f16 v[82:97], v[158:161], v[146:149], v[82:97]
	v_mfma_f32_32x32x16_f16 v[66:81], v[200:203], v[146:149], v[66:81]
	v_mfma_f32_32x32x16_f16 v[50:65], v[158:161], v[150:153], v[50:65]
	v_mfma_f32_32x32x16_f16 v[34:49], v[200:203], v[150:153], v[34:49]
	global_load_dwordx4 v[130:133], v[138:139], off offset:48
	global_load_dwordx4 v[134:137], v[138:139], off offset:32
	global_load_dwordx4 v[142:145], v[138:139], off offset:16
	global_load_dwordx4 v[150:153], v[138:139], off
	s_nop 0
	global_load_dwordx4 v[138:141], v[178:179], off offset:48
	global_load_dwordx4 v[146:149], v[178:179], off offset:32
	global_load_dwordx4 v[154:157], v[178:179], off offset:16
	s_waitcnt lgkmcnt(0)
	v_mfma_f32_32x32x16_f16 v[18:33], v[158:161], v[216:219], v[18:33]
	global_load_dwordx4 v[158:161], v[178:179], off
	s_barrier
	v_mfma_f32_32x32x16_f16 v[2:17], v[200:203], v[216:219], v[2:17]
	s_cbranch_scc0 .LBB0_1677
; DI f16v mfma32(h8v a, h8v b, f16v c) { return __builtin_amdgcn_mfma_f32_32x32x16_f16(a, b, c, 0, 0, 0); }
; template <bool GATHER>
; DI void gemm256_main(const h16* __restrict__ A, int lda, const int* __restrict__ idx, int m0,
;                      const h16* __restrict__ B, int ldb, int n0, int K, h16* lds, f16v (&acc)[4][2]) {
;     ...
;   for (int kt = 0; kt < nk; ++kt) {
;     const h16* As = lds + (kt & 1) * (512 * LDH);
;     const h16* Bs = As + 256 * LDH;
;     h16* Wn = lds + ((kt & 1) ^ 1) * (512 * LDH);
;     if (kt + 1 < nk) {
; #pragma unroll
;       for (int i = 0; i < 4; ++i) { *(u4v*)&Wn[lr * LDH + lc + 8 * i] = ra[i]; *(u4v*)&Wn[(256 + lr) * LDH + lc + 8 * i] = rb[i]; }
;     }
;     if (kt + 2 < nk) {
; #pragma unroll
;       for (int i = 0; i < 4; ++i) { ra[i] = *(const u4v*)(AP_ + 8 * i); rb[i] = *(const u4v*)(BP_ + 8 * i); }
;       ao += 64; bo += 64;
;     }
; #pragma unroll
;     for (int ks = 0; ks < 4; ++ks) {
;       h8v af[4], bf[2];
; #pragma unroll
;       for (int i = 0; i < 4; ++i) af[i] = *(const h8v*)&As[(wm * 128 + i * 32 + (lane & 31)) * LDH + ks * 16 + 8 * (lane >> 5)];
; #pragma unroll
;       for (int j = 0; j < 2; ++j) bf[j] = *(const h8v*)&Bs[(wn * 64 + j * 32 + (lane & 31)) * LDH + ks * 16 + 8 * (lane >> 5)];
; #pragma unroll
;       for (int i = 0; i < 4; ++i)
; #pragma unroll
;         for (int j = 0; j < 2; ++j) acc[i][j] = mfma32(bf[j], af[i], acc[i][j]);
;     }
;     __syncthreads();
;   }
	v_add_u32_e32 v162, 0x12000, v176
	v_add_u32_e32 v163, 0x1b000, v176
	s_waitcnt vmcnt(4)
	ds_write_b128 v162, v[150:153]
	s_waitcnt vmcnt(0)
	ds_write_b128 v163, v[158:161]
	ds_write_b128 v162, v[142:145] offset:16
	ds_write_b128 v163, v[154:157] offset:16
	ds_write_b128 v162, v[134:137] offset:32
	ds_write_b128 v163, v[146:149] offset:32
	ds_write_b128 v162, v[130:133] offset:48
	ds_write_b128 v163, v[138:141] offset:48
	v_add_u32_e32 v162, v175, v171
	v_add_u32_e32 v163, v175, v1
	ds_read_b128 v[130:133], v162 offset:4608
	ds_read_b128 v[134:137], v162 offset:9216
	ds_read_b128 v[138:141], v162 offset:13824
	ds_read_b128 v[142:145], v163 offset:41472
	ds_read_b128 v[146:149], v162
	ds_read_b128 v[150:153], v162 offset:32
	ds_read_b128 v[154:157], v163 offset:36864
	ds_read_b128 v[158:161], v163 offset:36896
	s_waitcnt lgkmcnt(1)
	v_mfma_f32_32x32x16_f16 v[114:129], v[154:157], v[146:149], v[114:129]
	s_add_i32 s5, 16, 0x12000
	s_add_i32 s6, 16, 0x1b000
	v_readlane_b32 s16, v252, 3
	v_readlane_b32 s18, v252, 5
	v_readlane_b32 s19, v252, 6
	v_readlane_b32 s22, v252, 9
	s_add_i32 s2, s2, s22
	v_mfma_f32_32x32x16_f16 v[98:113], v[142:145], v[146:149], v[98:113]
	s_cmpk_gt_i32 s2, 0xff
	v_readlane_b32 s17, v252, 4
	v_readlane_b32 s20, v252, 7
	v_readlane_b32 s21, v252, 8
	v_readlane_b32 s23, v252, 10
	v_mfma_f32_32x32x16_f16 v[18:33], v[154:157], v[138:141], v[18:33]
	v_mfma_f32_32x32x16_f16 v[2:17], v[142:145], v[138:141], v[2:17]
	v_mfma_f32_32x32x16_f16 v[82:97], v[154:157], v[130:133], v[82:97]
	v_mfma_f32_32x32x16_f16 v[66:81], v[142:145], v[130:133], v[66:81]
	v_mfma_f32_32x32x16_f16 v[50:65], v[154:157], v[134:137], v[50:65]
	v_mfma_f32_32x32x16_f16 v[34:49], v[142:145], v[134:137], v[34:49]
	ds_read_b128 v[130:133], v162 offset:4640
	ds_read_b128 v[134:137], v162 offset:9248
	ds_read_b128 v[138:141], v162 offset:13856
	ds_read_b128 v[142:145], v163 offset:41504
	s_waitcnt lgkmcnt(4)
	v_mfma_f32_32x32x16_f16 v[114:129], v[158:161], v[150:153], v[114:129]
	s_waitcnt lgkmcnt(0)
	v_mfma_f32_32x32x16_f16 v[98:113], v[142:145], v[150:153], v[98:113]
	v_mfma_f32_32x32x16_f16 v[18:33], v[158:161], v[138:141], v[18:33]
	v_mfma_f32_32x32x16_f16 v[2:17], v[142:145], v[138:141], v[2:17]
	v_mfma_f32_32x32x16_f16 v[82:97], v[158:161], v[130:133], v[82:97]
	v_mfma_f32_32x32x16_f16 v[66:81], v[142:145], v[130:133], v[66:81]
	v_mfma_f32_32x32x16_f16 v[50:65], v[158:161], v[134:137], v[50:65]
	v_mfma_f32_32x32x16_f16 v[34:49], v[142:145], v[134:137], v[34:49]
	ds_read_b128 v[130:133], v162 offset:64
	ds_read_b128 v[134:137], v162 offset:4672
	ds_read_b128 v[138:141], v162 offset:9280
	ds_read_b128 v[142:145], v162 offset:13888
	ds_read_b128 v[146:149], v163 offset:36928
	ds_read_b128 v[150:153], v163 offset:41536
	s_waitcnt lgkmcnt(1)
	v_mfma_f32_32x32x16_f16 v[114:129], v[146:149], v[130:133], v[114:129]
	s_waitcnt lgkmcnt(0)
	v_mfma_f32_32x32x16_f16 v[98:113], v[150:153], v[130:133], v[98:113]
	v_mfma_f32_32x32x16_f16 v[18:33], v[146:149], v[142:145], v[18:33]
	v_mfma_f32_32x32x16_f16 v[2:17], v[150:153], v[142:145], v[2:17]
	v_mfma_f32_32x32x16_f16 v[82:97], v[146:149], v[134:137], v[82:97]
	v_mfma_f32_32x32x16_f16 v[66:81], v[150:153], v[134:137], v[66:81]
	v_mfma_f32_32x32x16_f16 v[50:65], v[146:149], v[138:141], v[50:65]
	v_mfma_f32_32x32x16_f16 v[34:49], v[150:153], v[138:141], v[34:49]
	ds_read_b128 v[130:133], v162 offset:96
	ds_read_b128 v[134:137], v162 offset:4704
	ds_read_b128 v[138:141], v162 offset:9312
	ds_read_b128 v[142:145], v162 offset:13920
	ds_read_b128 v[146:149], v163 offset:36960
	ds_read_b128 v[150:153], v163 offset:41568
	s_waitcnt lgkmcnt(0)
	s_barrier
	v_mfma_f32_32x32x16_f16 v[114:129], v[146:149], v[130:133], v[114:129]
	v_mfma_f32_32x32x16_f16 v[98:113], v[150:153], v[130:133], v[98:113]
	v_mfma_f32_32x32x16_f16 v[18:33], v[146:149], v[142:145], v[18:33]
	v_mfma_f32_32x32x16_f16 v[2:17], v[150:153], v[142:145], v[2:17]
	v_lshlrev_b32_e32 v142, 1, v174
	v_add3_u32 v162, s5, v142, v171
	v_add3_u32 v1, s6, v142, v1
	v_mfma_f32_32x32x16_f16 v[82:97], v[146:149], v[134:137], v[82:97]
	v_mfma_f32_32x32x16_f16 v[66:81], v[150:153], v[134:137], v[66:81]
	v_mfma_f32_32x32x16_f16 v[50:65], v[146:149], v[138:141], v[50:65]
	v_mfma_f32_32x32x16_f16 v[34:49], v[150:153], v[138:141], v[34:49]
	ds_read_b128 v[130:133], v162 offset:4608
	ds_read_b128 v[134:137], v162 offset:9216
	ds_read_b128 v[138:141], v162 offset:13824
	ds_read_b128 v[142:145], v1 offset:4608
	ds_read_b128 v[146:149], v162
	ds_read_b128 v[150:153], v162 offset:32
	ds_read_b128 v[154:157], v1
	ds_read_b128 v[158:161], v1 offset:32
	s_waitcnt lgkmcnt(1)
	v_mfma_f32_32x32x16_f16 v[114:129], v[154:157], v[146:149], v[114:129]
	v_mfma_f32_32x32x16_f16 v[98:113], v[142:145], v[146:149], v[98:113]
	v_mfma_f32_32x32x16_f16 v[82:97], v[154:157], v[130:133], v[82:97]
	v_mfma_f32_32x32x16_f16 v[66:81], v[142:145], v[130:133], v[66:81]
	v_mfma_f32_32x32x16_f16 v[50:65], v[154:157], v[134:137], v[50:65]
	v_mfma_f32_32x32x16_f16 v[34:49], v[142:145], v[134:137], v[34:49]
	v_mfma_f32_32x32x16_f16 v[18:33], v[154:157], v[138:141], v[18:33]
	v_mfma_f32_32x32x16_f16 v[2:17], v[142:145], v[138:141], v[2:17]
	ds_read_b128 v[130:133], v162 offset:4640
	ds_read_b128 v[134:137], v162 offset:9248
	ds_read_b128 v[138:141], v162 offset:13856
	ds_read_b128 v[142:145], v1 offset:4640
	s_waitcnt lgkmcnt(4)
	v_mfma_f32_32x32x16_f16 v[114:129], v[158:161], v[150:153], v[114:129]
	s_waitcnt lgkmcnt(0)
; DI int otid512() { int t = threadIdx.x; asm volatile("" : "+v"(t)); return t; }
; template <class Epi>
; DI void gemm256_epilogue(f16v (&acc)[4][2], int m0, int n0, Epi epi) {
;   const int tid = otid512(), lane = tid & 63, wv = tid >> 6, wm = wv >> 2, wn = wv & 3, h = lane >> 5;
; #pragma unroll
;   for (int i = 0; i < 4; ++i) {
;     const int m = m0 + wm * 128 + i * 32 + (lane & 31);
; #pragma unroll
;     for (int g = 0; g < 4; ++g) {
;       const int n = n0 + wn * 64 + 8 * g + 4 * h;
;       f4v v0 = {acc[i][0][4 * g], acc[i][0][4 * g + 1], acc[i][0][4 * g + 2], acc[i][0][4 * g + 3]};
;       f4v v1 = {acc[i][1][4 * g], acc[i][1][4 * g + 1], acc[i][1][4 * g + 2], acc[i][1][4 * g + 3]};
;       epi(m, n, v0, v1);
;     }
;   }
; }
; DI void phase_resid_gemm(const Params& p, const h16* A, int lda, const h16* W, int K, const float* xres, int bid, int nb, h16* lds) {
;     ...
;     gemm256_epilogue(acc, m0, n0, [&](int m, int n, f4v v0, f4v v1) {
;       const f4v x0 = *(const f4v*)&xres[(size_t)m * DM + n], x1 = *(const f4v*)&xres[(size_t)m * DM + n + 32];
;       *(f4v*)&out[(size_t)m * DM + n] = ALPHA * x0 + v0;
;       *(f4v*)&out[(size_t)m * DM + n + 32] = ALPHA * x1 + v1;
;     });
	v_mfma_f32_32x32x16_f16 v[98:113], v[142:145], v[150:153], v[98:113]
	v_mfma_f32_32x32x16_f16 v[82:97], v[158:161], v[130:133], v[82:97]
	v_mfma_f32_32x32x16_f16 v[66:81], v[142:145], v[130:133], v[66:81]
	v_mfma_f32_32x32x16_f16 v[50:65], v[158:161], v[134:137], v[50:65]
	v_mfma_f32_32x32x16_f16 v[34:49], v[142:145], v[134:137], v[34:49]
	v_mfma_f32_32x32x16_f16 v[18:33], v[158:161], v[138:141], v[18:33]
	v_mfma_f32_32x32x16_f16 v[2:17], v[142:145], v[138:141], v[2:17]
	ds_read_b128 v[130:133], v162 offset:64
	ds_read_b128 v[134:137], v162 offset:4672
	ds_read_b128 v[138:141], v162 offset:9280
	ds_read_b128 v[142:145], v162 offset:13888
	ds_read_b128 v[146:149], v1 offset:64
	ds_read_b128 v[150:153], v1 offset:4672
	s_waitcnt lgkmcnt(1)
	v_mfma_f32_32x32x16_f16 v[114:129], v[146:149], v[130:133], v[114:129]
	s_waitcnt lgkmcnt(0)
	v_mfma_f32_32x32x16_f16 v[98:113], v[150:153], v[130:133], v[98:113]
	v_mfma_f32_32x32x16_f16 v[82:97], v[146:149], v[134:137], v[82:97]
	v_mfma_f32_32x32x16_f16 v[66:81], v[150:153], v[134:137], v[66:81]
	v_mfma_f32_32x32x16_f16 v[50:65], v[146:149], v[138:141], v[50:65]
	v_mfma_f32_32x32x16_f16 v[34:49], v[150:153], v[138:141], v[34:49]
	v_mfma_f32_32x32x16_f16 v[18:33], v[146:149], v[142:145], v[18:33]
	v_mfma_f32_32x32x16_f16 v[2:17], v[150:153], v[142:145], v[2:17]
	ds_read_b128 v[130:133], v162 offset:96
	ds_read_b128 v[134:137], v162 offset:4704
	ds_read_b128 v[138:141], v162 offset:9312
	ds_read_b128 v[142:145], v162 offset:13920
	ds_read_b128 v[146:149], v1 offset:96
	ds_read_b128 v[150:153], v1 offset:4704
	v_mov_b32_e32 v1, v180
	s_waitcnt lgkmcnt(0)
	s_barrier
	v_mfma_f32_32x32x16_f16 v[114:129], v[146:149], v[130:133], v[114:129]
	v_mfma_f32_32x32x16_f16 v[98:113], v[150:153], v[130:133], v[98:113]
	v_mfma_f32_32x32x16_f16 v[82:97], v[146:149], v[134:137], v[82:97]
	v_mfma_f32_32x32x16_f16 v[66:81], v[150:153], v[134:137], v[66:81]
	v_mfma_f32_32x32x16_f16 v[18:33], v[146:149], v[142:145], v[18:33]
	v_mfma_f32_32x32x16_f16 v[2:17], v[150:153], v[142:145], v[2:17]
	v_mfma_f32_32x32x16_f16 v[50:65], v[146:149], v[138:141], v[50:65]
	v_mfma_f32_32x32x16_f16 v[34:49], v[150:153], v[138:141], v[34:49]
	s_nop 15
	s_cselect_b32 s60, 1, 0
	s_barrier
	v_readfirstlane_b32 s66, v180
	s_mov_b32 s69, s3
	s_mov_b32 s65, s4
	s_lshr_b32 s66, s66, 6
	s_and_b32 s67, s66, 3
	s_lshr_b32 s68, s66, 2
	s_lshl_b32 s70, s67, 6
	s_add_i32 s70, s70, s69
	s_lshl_b32 s71, s68, 7
	s_add_i32 s71, s71, s65
	s_mul_i32 s72, s66, 0x4400
	s_add_i32 s72, s72, 16
	v_and_b32_e32 v136, 63, v180
	v_and_b32_e32 v137, 31, v136
	v_lshrrev_b32_e32 v138, 5, v136
	v_mul_u32_u24_e32 v130, 0x110, v137
	v_lshl_add_u32 v130, v138, 4, v130
	v_add_u32_e32 v130, s72, v130
	v_lshrrev_b32_e32 v137, 4, v136
	v_and_b32_e32 v138, 15, v136
	v_mul_u32_u24_e32 v131, 0x110, v137
	v_lshl_add_u32 v131, v138, 4, v131
	v_add_u32_e32 v131, s72, v131
	v_add_u32_e32 v137, s71, v137
	v_lshl_add_u32 v138, v138, 2, s70
	v_lshlrev_b32_e32 v138, 2, v138
	v_mov_b32_e32 v139, v0
	s_mov_b32 s73, 0x1000
	v_mov_b64_e32 v[132:133], s[18:19]
	v_mad_u64_u32 v[132:133], s[74:75], v137, s73, v[132:133]
	v_lshl_add_u64 v[132:133], v[132:133], 0, v[138:139]
	v_mov_b64_e32 v[134:135], s[18:19]
	v_mad_u64_u32 v[134:135], s[74:75], v137, s73, v[134:135]
	v_lshl_add_u64 v[134:135], v[134:135], 0, v[138:139]
	s_mov_b32 s76, 0x4000
	s_mov_b32 s77, 0
	ds_write_b128 v130, v[114:117]
	ds_write_b128 v130, v[118:121] offset:32
	ds_write_b128 v130, v[122:125] offset:64
	ds_write_b128 v130, v[126:129] offset:96
	ds_write_b128 v130, v[98:101] offset:128
	ds_write_b128 v130, v[102:105] offset:160
	ds_write_b128 v130, v[106:109] offset:192
	ds_write_b128 v130, v[110:113] offset:224
	ds_write_b128 v130, v[82:85] offset:8704
	ds_write_b128 v130, v[86:89] offset:8736
	ds_write_b128 v130, v[90:93] offset:8768
	ds_write_b128 v130, v[94:97] offset:8800
	ds_write_b128 v130, v[66:69] offset:8832
	ds_write_b128 v130, v[70:73] offset:8864
	ds_write_b128 v130, v[74:77] offset:8896
	ds_write_b128 v130, v[78:81] offset:8928
	global_load_dwordx4 v[224:227], v[132:133], off
	v_lshl_add_u64 v[132:133], v[132:133], 0, s[76:77]
	global_load_dwordx4 v[228:231], v[132:133], off
	v_lshl_add_u64 v[132:133], v[132:133], 0, s[76:77]
	global_load_dwordx4 v[232:235], v[132:133], off
	v_lshl_add_u64 v[132:133], v[132:133], 0, s[76:77]
	global_load_dwordx4 v[236:239], v[132:133], off
	v_lshl_add_u64 v[132:133], v[132:133], 0, s[76:77]
	global_load_dwordx4 v[240:243], v[132:133], off
	v_lshl_add_u64 v[132:133], v[132:133], 0, s[76:77]
	global_load_dwordx4 v[244:247], v[132:133], off
	v_lshl_add_u64 v[132:133], v[132:133], 0, s[76:77]
	global_load_dwordx4 v[176:179], v[132:133], off
	v_lshl_add_u64 v[132:133], v[132:133], 0, s[76:77]
	global_load_dwordx4 v[200:203], v[132:133], off
	v_lshl_add_u64 v[132:133], v[132:133], 0, s[76:77]
	ds_read_b128 v[140:143], v131
	ds_read_b128 v[144:147], v131 offset:1088
	ds_read_b128 v[148:151], v131 offset:2176
	ds_read_b128 v[152:155], v131 offset:3264
	ds_read_b128 v[156:159], v131 offset:4352
	ds_read_b128 v[160:163], v131 offset:5440
	ds_read_b128 v[216:219], v131 offset:6528
	ds_read_b128 v[220:223], v131 offset:7616
	s_waitcnt vmcnt(7) lgkmcnt(7)
	v_pk_fma_f32 v[140:141], v[224:225], s[10:11], v[140:141] op_sel_hi:[1,0,1]
	v_pk_fma_f32 v[142:143], v[226:227], s[10:11], v[142:143] op_sel_hi:[1,0,1]
	global_store_dwordx4 v[134:135], v[140:143], off
	v_lshl_add_u64 v[134:135], v[134:135], 0, s[76:77]
	s_waitcnt vmcnt(7) lgkmcnt(6)
	v_pk_fma_f32 v[144:145], v[228:229], s[10:11], v[144:145] op_sel_hi:[1,0,1]
	v_pk_fma_f32 v[146:147], v[230:231], s[10:11], v[146:147] op_sel_hi:[1,0,1]
	global_store_dwordx4 v[134:135], v[144:147], off
	v_lshl_add_u64 v[134:135], v[134:135], 0, s[76:77]
	s_waitcnt vmcnt(7) lgkmcnt(5)
; DI int otid512() { int t = threadIdx.x; asm volatile("" : "+v"(t)); return t; }
; template <class Epi>
; DI void gemm256_epilogue(f16v (&acc)[4][2], int m0, int n0, Epi epi) {
;   const int tid = otid512(), lane = tid & 63, wv = tid >> 6, wm = wv >> 2, wn = wv & 3, h = lane >> 5;
; #pragma unroll
;   for (int i = 0; i < 4; ++i) {
;     const int m = m0 + wm * 128 + i * 32 + (lane & 31);
; #pragma unroll
;     for (int g = 0; g < 4; ++g) {
;       const int n = n0 + wn * 64 + 8 * g + 4 * h;
;       f4v v0 = {acc[i][0][4 * g], acc[i][0][4 * g + 1], acc[i][0][4 * g + 2], acc[i][0][4 * g + 3]};
;       f4v v1 = {acc[i][1][4 * g], acc[i][1][4 * g + 1], acc[i][1][4 * g + 2], acc[i][1][4 * g + 3]};
;       epi(m, n, v0, v1);
;     }
;   }
; }
; DI void phase_resid_gemm(const Params& p, const h16* A, int lda, const h16* W, int K, const float* xres, int bid, int nb, h16* lds) {
;     ...
;     gemm256_epilogue(acc, m0, n0, [&](int m, int n, f4v v0, f4v v1) {
;       const f4v x0 = *(const f4v*)&xres[(size_t)m * DM + n], x1 = *(const f4v*)&xres[(size_t)m * DM + n + 32];
;       *(f4v*)&out[(size_t)m * DM + n] = ALPHA * x0 + v0;
;       *(f4v*)&out[(size_t)m * DM + n + 32] = ALPHA * x1 + v1;
;     });
	v_pk_fma_f32 v[148:149], v[232:233], s[10:11], v[148:149] op_sel_hi:[1,0,1]
	v_pk_fma_f32 v[150:151], v[234:235], s[10:11], v[150:151] op_sel_hi:[1,0,1]
	global_store_dwordx4 v[134:135], v[148:151], off
	v_lshl_add_u64 v[134:135], v[134:135], 0, s[76:77]
	s_waitcnt vmcnt(7) lgkmcnt(4)
	v_pk_fma_f32 v[152:153], v[236:237], s[10:11], v[152:153] op_sel_hi:[1,0,1]
	v_pk_fma_f32 v[154:155], v[238:239], s[10:11], v[154:155] op_sel_hi:[1,0,1]
	global_store_dwordx4 v[134:135], v[152:155], off
	v_lshl_add_u64 v[134:135], v[134:135], 0, s[76:77]
	s_waitcnt vmcnt(7) lgkmcnt(3)
	v_pk_fma_f32 v[156:157], v[240:241], s[10:11], v[156:157] op_sel_hi:[1,0,1]
	v_pk_fma_f32 v[158:159], v[242:243], s[10:11], v[158:159] op_sel_hi:[1,0,1]
	global_store_dwordx4 v[134:135], v[156:159], off
	v_lshl_add_u64 v[134:135], v[134:135], 0, s[76:77]
	s_waitcnt vmcnt(7) lgkmcnt(2)
	v_pk_fma_f32 v[160:161], v[244:245], s[10:11], v[160:161] op_sel_hi:[1,0,1]
	v_pk_fma_f32 v[162:163], v[246:247], s[10:11], v[162:163] op_sel_hi:[1,0,1]
	global_store_dwordx4 v[134:135], v[160:163], off
	v_lshl_add_u64 v[134:135], v[134:135], 0, s[76:77]
	s_waitcnt vmcnt(7) lgkmcnt(1)
	v_pk_fma_f32 v[216:217], v[176:177], s[10:11], v[216:217] op_sel_hi:[1,0,1]
	v_pk_fma_f32 v[218:219], v[178:179], s[10:11], v[218:219] op_sel_hi:[1,0,1]
	global_store_dwordx4 v[134:135], v[216:219], off
	v_lshl_add_u64 v[134:135], v[134:135], 0, s[76:77]
	s_waitcnt vmcnt(7) lgkmcnt(0)
	v_pk_fma_f32 v[220:221], v[200:201], s[10:11], v[220:221] op_sel_hi:[1,0,1]
	v_pk_fma_f32 v[222:223], v[202:203], s[10:11], v[222:223] op_sel_hi:[1,0,1]
	global_store_dwordx4 v[134:135], v[220:223], off
	v_lshl_add_u64 v[134:135], v[134:135], 0, s[76:77]
	s_nop 1
	global_load_dwordx4 v[224:227], v[132:133], off
	v_lshl_add_u64 v[132:133], v[132:133], 0, s[76:77]
	global_load_dwordx4 v[228:231], v[132:133], off
	v_lshl_add_u64 v[132:133], v[132:133], 0, s[76:77]
	global_load_dwordx4 v[232:235], v[132:133], off
	v_lshl_add_u64 v[132:133], v[132:133], 0, s[76:77]
	global_load_dwordx4 v[236:239], v[132:133], off
	v_lshl_add_u64 v[132:133], v[132:133], 0, s[76:77]
	global_load_dwordx4 v[240:243], v[132:133], off
	v_lshl_add_u64 v[132:133], v[132:133], 0, s[76:77]
	global_load_dwordx4 v[244:247], v[132:133], off
	v_lshl_add_u64 v[132:133], v[132:133], 0, s[76:77]
	global_load_dwordx4 v[176:179], v[132:133], off
	v_lshl_add_u64 v[132:133], v[132:133], 0, s[76:77]
	global_load_dwordx4 v[200:203], v[132:133], off
	v_lshl_add_u64 v[132:133], v[132:133], 0, s[76:77]
	ds_read_b128 v[140:143], v131 offset:8704
	ds_read_b128 v[144:147], v131 offset:9792
	ds_read_b128 v[148:151], v131 offset:10880
	ds_read_b128 v[152:155], v131 offset:11968
	ds_read_b128 v[156:159], v131 offset:13056
	ds_read_b128 v[160:163], v131 offset:14144
	ds_read_b128 v[216:219], v131 offset:15232
	ds_read_b128 v[220:223], v131 offset:16320
	s_waitcnt vmcnt(7) lgkmcnt(7)
	v_pk_fma_f32 v[140:141], v[224:225], s[10:11], v[140:141] op_sel_hi:[1,0,1]
	v_pk_fma_f32 v[142:143], v[226:227], s[10:11], v[142:143] op_sel_hi:[1,0,1]
	global_store_dwordx4 v[134:135], v[140:143], off
	v_lshl_add_u64 v[134:135], v[134:135], 0, s[76:77]
	s_waitcnt vmcnt(7) lgkmcnt(6)
	v_pk_fma_f32 v[144:145], v[228:229], s[10:11], v[144:145] op_sel_hi:[1,0,1]
	v_pk_fma_f32 v[146:147], v[230:231], s[10:11], v[146:147] op_sel_hi:[1,0,1]
	global_store_dwordx4 v[134:135], v[144:147], off
	v_lshl_add_u64 v[134:135], v[134:135], 0, s[76:77]
	s_waitcnt vmcnt(7) lgkmcnt(5)
	v_pk_fma_f32 v[148:149], v[232:233], s[10:11], v[148:149] op_sel_hi:[1,0,1]
	v_pk_fma_f32 v[150:151], v[234:235], s[10:11], v[150:151] op_sel_hi:[1,0,1]
	global_store_dwordx4 v[134:135], v[148:151], off
	v_lshl_add_u64 v[134:135], v[134:135], 0, s[76:77]
	s_waitcnt vmcnt(7) lgkmcnt(4)
	v_pk_fma_f32 v[152:153], v[236:237], s[10:11], v[152:153] op_sel_hi:[1,0,1]
	v_pk_fma_f32 v[154:155], v[238:239], s[10:11], v[154:155] op_sel_hi:[1,0,1]
	global_store_dwordx4 v[134:135], v[152:155], off
	v_lshl_add_u64 v[134:135], v[134:135], 0, s[76:77]
	s_waitcnt vmcnt(7) lgkmcnt(3)
	v_pk_fma_f32 v[156:157], v[240:241], s[10:11], v[156:157] op_sel_hi:[1,0,1]
	v_pk_fma_f32 v[158:159], v[242:243], s[10:11], v[158:159] op_sel_hi:[1,0,1]
	global_store_dwordx4 v[134:135], v[156:159], off
	v_lshl_add_u64 v[134:135], v[134:135], 0, s[76:77]
	s_waitcnt vmcnt(7) lgkmcnt(2)
	v_pk_fma_f32 v[160:161], v[244:245], s[10:11], v[160:161] op_sel_hi:[1,0,1]
	v_pk_fma_f32 v[162:163], v[246:247], s[10:11], v[162:163] op_sel_hi:[1,0,1]
	global_store_dwordx4 v[134:135], v[160:163], off
	v_lshl_add_u64 v[134:135], v[134:135], 0, s[76:77]
	s_waitcnt vmcnt(7) lgkmcnt(1)
	v_pk_fma_f32 v[216:217], v[176:177], s[10:11], v[216:217] op_sel_hi:[1,0,1]
	v_pk_fma_f32 v[218:219], v[178:179], s[10:11], v[218:219] op_sel_hi:[1,0,1]
	global_store_dwordx4 v[134:135], v[216:219], off
	v_lshl_add_u64 v[134:135], v[134:135], 0, s[76:77]
	s_waitcnt vmcnt(7) lgkmcnt(0)
; DI int otid512() { int t = threadIdx.x; asm volatile("" : "+v"(t)); return t; }
; template <class Epi>
; DI void gemm256_epilogue(f16v (&acc)[4][2], int m0, int n0, Epi epi) {
;   const int tid = otid512(), lane = tid & 63, wv = tid >> 6, wm = wv >> 2, wn = wv & 3, h = lane >> 5;
; #pragma unroll
;   for (int i = 0; i < 4; ++i) {
;     const int m = m0 + wm * 128 + i * 32 + (lane & 31);
; #pragma unroll
;     for (int g = 0; g < 4; ++g) {
;       const int n = n0 + wn * 64 + 8 * g + 4 * h;
;       f4v v0 = {acc[i][0][4 * g], acc[i][0][4 * g + 1], acc[i][0][4 * g + 2], acc[i][0][4 * g + 3]};
;       f4v v1 = {acc[i][1][4 * g], acc[i][1][4 * g + 1], acc[i][1][4 * g + 2], acc[i][1][4 * g + 3]};
;       epi(m, n, v0, v1);
;     }
;   }
; }
; DI void phase_resid_gemm(const Params& p, const h16* A, int lda, const h16* W, int K, const float* xres, int bid, int nb, h16* lds) {
;     ...
;     gemm256_epilogue(acc, m0, n0, [&](int m, int n, f4v v0, f4v v1) {
;       const f4v x0 = *(const f4v*)&xres[(size_t)m * DM + n], x1 = *(const f4v*)&xres[(size_t)m * DM + n + 32];
;       *(f4v*)&out[(size_t)m * DM + n] = ALPHA * x0 + v0;
;       *(f4v*)&out[(size_t)m * DM + n + 32] = ALPHA * x1 + v1;
;     });
	v_pk_fma_f32 v[220:221], v[200:201], s[10:11], v[220:221] op_sel_hi:[1,0,1]
	v_pk_fma_f32 v[222:223], v[202:203], s[10:11], v[222:223] op_sel_hi:[1,0,1]
	global_store_dwordx4 v[134:135], v[220:223], off
	v_lshl_add_u64 v[134:135], v[134:135], 0, s[76:77]
	s_nop 1
	ds_write_b128 v130, v[50:53]
	ds_write_b128 v130, v[54:57] offset:32
	ds_write_b128 v130, v[58:61] offset:64
	ds_write_b128 v130, v[62:65] offset:96
	ds_write_b128 v130, v[34:37] offset:128
	ds_write_b128 v130, v[38:41] offset:160
	ds_write_b128 v130, v[42:45] offset:192
	ds_write_b128 v130, v[46:49] offset:224
	ds_write_b128 v130, v[18:21] offset:8704
	ds_write_b128 v130, v[22:25] offset:8736
	ds_write_b128 v130, v[26:29] offset:8768
	ds_write_b128 v130, v[30:33] offset:8800
	ds_write_b128 v130, v[2:5] offset:8832
	ds_write_b128 v130, v[6:9] offset:8864
	ds_write_b128 v130, v[10:13] offset:8896
	ds_write_b128 v130, v[14:17] offset:8928
	global_load_dwordx4 v[224:227], v[132:133], off
	v_lshl_add_u64 v[132:133], v[132:133], 0, s[76:77]
	global_load_dwordx4 v[228:231], v[132:133], off
	v_lshl_add_u64 v[132:133], v[132:133], 0, s[76:77]
	global_load_dwordx4 v[232:235], v[132:133], off
	v_lshl_add_u64 v[132:133], v[132:133], 0, s[76:77]
	global_load_dwordx4 v[236:239], v[132:133], off
	v_lshl_add_u64 v[132:133], v[132:133], 0, s[76:77]
	global_load_dwordx4 v[240:243], v[132:133], off
	v_lshl_add_u64 v[132:133], v[132:133], 0, s[76:77]
	global_load_dwordx4 v[244:247], v[132:133], off
	v_lshl_add_u64 v[132:133], v[132:133], 0, s[76:77]
	global_load_dwordx4 v[176:179], v[132:133], off
	v_lshl_add_u64 v[132:133], v[132:133], 0, s[76:77]
	global_load_dwordx4 v[200:203], v[132:133], off
	v_lshl_add_u64 v[132:133], v[132:133], 0, s[76:77]
	ds_read_b128 v[140:143], v131
	ds_read_b128 v[144:147], v131 offset:1088
	ds_read_b128 v[148:151], v131 offset:2176
	ds_read_b128 v[152:155], v131 offset:3264
	ds_read_b128 v[156:159], v131 offset:4352
	ds_read_b128 v[160:163], v131 offset:5440
	ds_read_b128 v[216:219], v131 offset:6528
	ds_read_b128 v[220:223], v131 offset:7616
	s_waitcnt vmcnt(7) lgkmcnt(7)
	v_pk_fma_f32 v[140:141], v[224:225], s[10:11], v[140:141] op_sel_hi:[1,0,1]
	v_pk_fma_f32 v[142:143], v[226:227], s[10:11], v[142:143] op_sel_hi:[1,0,1]
	global_store_dwordx4 v[134:135], v[140:143], off
	v_lshl_add_u64 v[134:135], v[134:135], 0, s[76:77]
	s_waitcnt vmcnt(7) lgkmcnt(6)
	v_pk_fma_f32 v[144:145], v[228:229], s[10:11], v[144:145] op_sel_hi:[1,0,1]
	v_pk_fma_f32 v[146:147], v[230:231], s[10:11], v[146:147] op_sel_hi:[1,0,1]
	global_store_dwordx4 v[134:135], v[144:147], off
	v_lshl_add_u64 v[134:135], v[134:135], 0, s[76:77]
	s_waitcnt vmcnt(7) lgkmcnt(5)
	v_pk_fma_f32 v[148:149], v[232:233], s[10:11], v[148:149] op_sel_hi:[1,0,1]
	v_pk_fma_f32 v[150:151], v[234:235], s[10:11], v[150:151] op_sel_hi:[1,0,1]
	global_store_dwordx4 v[134:135], v[148:151], off
	v_lshl_add_u64 v[134:135], v[134:135], 0, s[76:77]
	s_waitcnt vmcnt(7) lgkmcnt(4)
	v_pk_fma_f32 v[152:153], v[236:237], s[10:11], v[152:153] op_sel_hi:[1,0,1]
	v_pk_fma_f32 v[154:155], v[238:239], s[10:11], v[154:155] op_sel_hi:[1,0,1]
	global_store_dwordx4 v[134:135], v[152:155], off
	v_lshl_add_u64 v[134:135], v[134:135], 0, s[76:77]
	s_waitcnt vmcnt(7) lgkmcnt(3)
	v_pk_fma_f32 v[156:157], v[240:241], s[10:11], v[156:157] op_sel_hi:[1,0,1]
	v_pk_fma_f32 v[158:159], v[242:243], s[10:11], v[158:159] op_sel_hi:[1,0,1]
	global_store_dwordx4 v[134:135], v[156:159], off
	v_lshl_add_u64 v[134:135], v[134:135], 0, s[76:77]
	s_waitcnt vmcnt(7) lgkmcnt(2)
	v_pk_fma_f32 v[160:161], v[244:245], s[10:11], v[160:161] op_sel_hi:[1,0,1]
	v_pk_fma_f32 v[162:163], v[246:247], s[10:11], v[162:163] op_sel_hi:[1,0,1]
	global_store_dwordx4 v[134:135], v[160:163], off
	v_lshl_add_u64 v[134:135], v[134:135], 0, s[76:77]
	s_waitcnt vmcnt(7) lgkmcnt(1)
; DI int otid512() { int t = threadIdx.x; asm volatile("" : "+v"(t)); return t; }
; template <class Epi>
; DI void gemm256_epilogue(f16v (&acc)[4][2], int m0, int n0, Epi epi) {
;   const int tid = otid512(), lane = tid & 63, wv = tid >> 6, wm = wv >> 2, wn = wv & 3, h = lane >> 5;
; #pragma unroll
;   for (int i = 0; i < 4; ++i) {
;     const int m = m0 + wm * 128 + i * 32 + (lane & 31);
; #pragma unroll
;     for (int g = 0; g < 4; ++g) {
;       const int n = n0 + wn * 64 + 8 * g + 4 * h;
;       f4v v0 = {acc[i][0][4 * g], acc[i][0][4 * g + 1], acc[i][0][4 * g + 2], acc[i][0][4 * g + 3]};
;       f4v v1 = {acc[i][1][4 * g], acc[i][1][4 * g + 1], acc[i][1][4 * g + 2], acc[i][1][4 * g + 3]};
;       epi(m, n, v0, v1);
;     }
;   }
; }
; DI void phase_resid_gemm(const Params& p, const h16* A, int lda, const h16* W, int K, const float* xres, int bid, int nb, h16* lds) {
;     ...
;     gemm256_epilogue(acc, m0, n0, [&](int m, int n, f4v v0, f4v v1) {
;       const f4v x0 = *(const f4v*)&xres[(size_t)m * DM + n], x1 = *(const f4v*)&xres[(size_t)m * DM + n + 32];
;       *(f4v*)&out[(size_t)m * DM + n] = ALPHA * x0 + v0;
;       *(f4v*)&out[(size_t)m * DM + n + 32] = ALPHA * x1 + v1;
;     });
	v_pk_fma_f32 v[216:217], v[176:177], s[10:11], v[216:217] op_sel_hi:[1,0,1]
	v_pk_fma_f32 v[218:219], v[178:179], s[10:11], v[218:219] op_sel_hi:[1,0,1]
	global_store_dwordx4 v[134:135], v[216:219], off
	v_lshl_add_u64 v[134:135], v[134:135], 0, s[76:77]
	s_waitcnt vmcnt(7) lgkmcnt(0)
	v_pk_fma_f32 v[220:221], v[200:201], s[10:11], v[220:221] op_sel_hi:[1,0,1]
	v_pk_fma_f32 v[222:223], v[202:203], s[10:11], v[222:223] op_sel_hi:[1,0,1]
	global_store_dwordx4 v[134:135], v[220:223], off
	v_lshl_add_u64 v[134:135], v[134:135], 0, s[76:77]
	s_nop 1
	global_load_dwordx4 v[224:227], v[132:133], off
	v_lshl_add_u64 v[132:133], v[132:133], 0, s[76:77]
	global_load_dwordx4 v[228:231], v[132:133], off
	v_lshl_add_u64 v[132:133], v[132:133], 0, s[76:77]
	global_load_dwordx4 v[232:235], v[132:133], off
	v_lshl_add_u64 v[132:133], v[132:133], 0, s[76:77]
	global_load_dwordx4 v[236:239], v[132:133], off
	v_lshl_add_u64 v[132:133], v[132:133], 0, s[76:77]
	global_load_dwordx4 v[240:243], v[132:133], off
	v_lshl_add_u64 v[132:133], v[132:133], 0, s[76:77]
	global_load_dwordx4 v[244:247], v[132:133], off
	v_lshl_add_u64 v[132:133], v[132:133], 0, s[76:77]
	global_load_dwordx4 v[176:179], v[132:133], off
	v_lshl_add_u64 v[132:133], v[132:133], 0, s[76:77]
	global_load_dwordx4 v[200:203], v[132:133], off
	v_lshl_add_u64 v[132:133], v[132:133], 0, s[76:77]
	ds_read_b128 v[140:143], v131 offset:8704
	ds_read_b128 v[144:147], v131 offset:9792
	ds_read_b128 v[148:151], v131 offset:10880
	ds_read_b128 v[152:155], v131 offset:11968
	ds_read_b128 v[156:159], v131 offset:13056
	ds_read_b128 v[160:163], v131 offset:14144
	ds_read_b128 v[216:219], v131 offset:15232
	ds_read_b128 v[220:223], v131 offset:16320
	s_waitcnt vmcnt(7) lgkmcnt(7)
	v_pk_fma_f32 v[140:141], v[224:225], s[10:11], v[140:141] op_sel_hi:[1,0,1]
	v_pk_fma_f32 v[142:143], v[226:227], s[10:11], v[142:143] op_sel_hi:[1,0,1]
	global_store_dwordx4 v[134:135], v[140:143], off
	v_lshl_add_u64 v[134:135], v[134:135], 0, s[76:77]
	s_waitcnt vmcnt(7) lgkmcnt(6)
	v_pk_fma_f32 v[144:145], v[228:229], s[10:11], v[144:145] op_sel_hi:[1,0,1]
	v_pk_fma_f32 v[146:147], v[230:231], s[10:11], v[146:147] op_sel_hi:[1,0,1]
	global_store_dwordx4 v[134:135], v[144:147], off
	v_lshl_add_u64 v[134:135], v[134:135], 0, s[76:77]
	s_waitcnt vmcnt(7) lgkmcnt(5)
	v_pk_fma_f32 v[148:149], v[232:233], s[10:11], v[148:149] op_sel_hi:[1,0,1]
	v_pk_fma_f32 v[150:151], v[234:235], s[10:11], v[150:151] op_sel_hi:[1,0,1]
	global_store_dwordx4 v[134:135], v[148:151], off
	v_lshl_add_u64 v[134:135], v[134:135], 0, s[76:77]
	s_waitcnt vmcnt(7) lgkmcnt(4)
	v_pk_fma_f32 v[152:153], v[236:237], s[10:11], v[152:153] op_sel_hi:[1,0,1]
	v_pk_fma_f32 v[154:155], v[238:239], s[10:11], v[154:155] op_sel_hi:[1,0,1]
	global_store_dwordx4 v[134:135], v[152:155], off
	v_lshl_add_u64 v[134:135], v[134:135], 0, s[76:77]
	s_waitcnt vmcnt(7) lgkmcnt(3)
	v_pk_fma_f32 v[156:157], v[240:241], s[10:11], v[156:157] op_sel_hi:[1,0,1]
	v_pk_fma_f32 v[158:159], v[242:243], s[10:11], v[158:159] op_sel_hi:[1,0,1]
	global_store_dwordx4 v[134:135], v[156:159], off
	v_lshl_add_u64 v[134:135], v[134:135], 0, s[76:77]
	s_waitcnt vmcnt(7) lgkmcnt(2)
	v_pk_fma_f32 v[160:161], v[244:245], s[10:11], v[160:161] op_sel_hi:[1,0,1]
	v_pk_fma_f32 v[162:163], v[246:247], s[10:11], v[162:163] op_sel_hi:[1,0,1]
	global_store_dwordx4 v[134:135], v[160:163], off
	v_lshl_add_u64 v[134:135], v[134:135], 0, s[76:77]
	s_waitcnt vmcnt(7) lgkmcnt(1)
	v_pk_fma_f32 v[216:217], v[176:177], s[10:11], v[216:217] op_sel_hi:[1,0,1]
	v_pk_fma_f32 v[218:219], v[178:179], s[10:11], v[218:219] op_sel_hi:[1,0,1]
	global_store_dwordx4 v[134:135], v[216:219], off
	v_lshl_add_u64 v[134:135], v[134:135], 0, s[76:77]
	s_waitcnt vmcnt(7) lgkmcnt(0)
	v_pk_fma_f32 v[220:221], v[200:201], s[10:11], v[220:221] op_sel_hi:[1,0,1]
	v_pk_fma_f32 v[222:223], v[202:203], s[10:11], v[222:223] op_sel_hi:[1,0,1]
	global_store_dwordx4 v[134:135], v[220:223], off
	v_lshl_add_u64 v[134:135], v[134:135], 0, s[76:77]
	s_nop 1
	s_cmp_eq_u32 s60, 1
	s_cbranch_scc0 .LBB0_1676
